# peel + first-K-tile LDS fragment reads issued at the top of the per-unit header (before next-unit scheduler math), all 9 GEMMs
# speedup vs baseline: 1.0011x; 1.0011x over previous
; #define PG8_STAGE(bufoff, gbase, voff) do { _Pragma("unroll") for (int _i = 0; _i < 2; ++_i) \
;         __builtin_amdgcn_global_load_lds((const unsigned*)((const char*)(gbase) + (voff)[_i]), (PG8_LAS unsigned*)(lds + (bufoff) + ldsw + _i * 8192), 16, 0, PG8_LOAD_AUX); } while (0)
; #define PG8_LDA(dst, b, h) do { _Pragma("unroll") for (int m = 0; m < 4; ++m) _Pragma("unroll") for (int k = 0; k < 2; ++k) dst[m][k] = *(const PG8_LAS bf16x8*)(lds + PG8_SA(b, h) + aoff + m * 2048 + k * 1024); } while (0)
; #define PG8_LDB(dst, b, h) do { _Pragma("unroll") for (int n = 0; n < 2; ++n) _Pragma("unroll") for (int k = 0; k < 2; ++k) dst[n][k] = *(const PG8_LAS bf16x8*)(lds + PG8_SB(b, h) + boff + n * 2048 + k * 1024); } while (0)
; #define PG8_SCHED __builtin_amdgcn_sched_barrier(0)
;     __host__ __device__ bool next(int i, Unit& u) const {
;         const long L = (long)i * G + c; if (L >= nwg) return false;
;         int wgid = (int)L; { const int q = nwg / NXCD, r = nwg % NXCD, xcd = wgid % NXCD, off = wgid / NXCD; wgid = (xcd < r ? xcd * (q + 1) : r * (q + 1) + (xcd - r) * q) + off; }
;         const int nig = WGM * nN, gid = wgid / nig, fm = gid * WGM, gsz = (nM - fm) < WGM ? (nM - fm) : WGM;
;         u.pm = fm + ((wgid % nig) % gsz); u.pn = (wgid % nig) / gsz; return true;
; template <class Epi, class Sched, bool ALIGN_EPI = false, bool SP2 = false>
; __device__ __forceinline__ void gemm_phase(PG8_LAS unsigned char* lds, const Gemm g, const Sched& S, const Epi& E) {
;     ...
;         const bool has_next = S.next(ui + 1, nxt);
;         const char* nA = has_next ? (const char*)g.A + (size_t)nxt.pm * tstepA + (size_t)nxt.pn * apn : cA; const char* nB = has_next ? (const char*)g.Bt + (size_t)nxt.pn * tstepB : cB;
;         for (int t = 0; t < nt; t += 2) {
;             const bool last = (t == nt - 2);
;             const char* a1 = cA + (size_t)(t + 1) * kstep;
;             const char* a2 = last ? nA : cA + (size_t)(t + 2) * kstep; const char* b2 = last ? nB : cB + (size_t)(t + 2) * kstep;
;             const char* a3 = a2 + kstep; const char* b3 = b2 + kstep;
;             if (last && has_next) S.a_ready(nxt);
;             if constexpr (SP2) {
;             PG8_LDB(B0, 0, 0); PG8_LDB(B1, 0, 1); PG8_SCHED; PG8_LDA(At, 0, 0); PG8_STAGE(PG8_SA(1, 1), a1 + hstepA, voffA);
.LBB0_212:
	ds_read_b128 v[162:165], v158
	ds_read_b128 v[166:169], v158 offset:1024
	ds_read_b128 v[170:173], v158 offset:2048
	ds_read_b128 v[174:177], v158 offset:3072
	ds_read_b128 v[178:181], v159
	ds_read_b128 v[182:185], v159 offset:1024
	ds_read_b128 v[186:189], v159 offset:2048
	ds_read_b128 v[190:193], v159 offset:3072
	ds_read_b128 v[194:197], v160
	ds_read_b128 v[198:201], v160 offset:1024
	ds_read_b128 v[202:205], v160 offset:2048
	ds_read_b128 v[206:209], v160 offset:3072
	ds_read_b128 v[210:213], v160 offset:4096
	ds_read_b128 v[214:217], v160 offset:5120
	ds_read_b128 v[218:221], v160 offset:6144
	ds_read_b128 v[222:225], v160 offset:7168
	s_add_i32 s46, s46, 1
	s_mul_i32 s4, s46, s47
	s_mul_hi_u32 s5, s46, s50
	s_add_i32 s5, s5, s4
	s_mul_i32 s4, s46, s50
	v_readlane_b32 s15, v239, 0
	s_add_u32 s18, s4, s15
	s_addc_u32 s19, s5, s36
	v_cmp_gt_i64_e32 vcc, s[18:19], v[144:145]
	v_cmp_lt_i64_e64 s[4:5], s[18:19], v[142:143]
	s_cbranch_vccnz .LBB0_214
	s_ashr_i32 s14, s18, 31
	s_lshr_b32 s14, s14, 29
	s_add_i32 s14, s18, s14
	s_ashr_i32 s15, s14, 3
	s_and_b32 s14, s14, -8
	s_sub_i32 s14, s18, s14
	s_cmp_lt_i32 s14, 0
	s_cselect_b32 s16, s37, 0x120
	s_mul_i32 s14, s14, s16
	s_add_i32 s14, s14, s15
	s_mul_hi_i32 s15, s14, 0x38e38e39
	s_lshr_b32 s16, s15, 31
	s_ashr_i32 s15, s15, 5
	s_add_i32 s15, s15, s16
	s_lshl_b32 s16, s15, 2
	s_sub_i32 s17, 64, s16
	s_min_i32 s17, s17, 4
	s_abs_i32 s18, s17
	v_cvt_f32_u32_e32 v0, s18
	s_sub_i32 s24, 0, s18
	s_mulk_i32 s15, 0x90
	s_sub_i32 s15, s14, s15
	v_rcp_iflag_f32_e32 v0, v0
	s_abs_i32 s14, s15
	s_xor_b32 s19, s15, s17
	s_ashr_i32 s19, s19, 31
	v_mul_f32_e32 v0, 0x4f7ffffe, v0
	v_cvt_u32_f32_e32 v0, v0
	s_nop 0
	v_readfirstlane_b32 s25, v0
	s_mul_i32 s24, s24, s25
	s_mul_hi_u32 s24, s25, s24
	s_add_i32 s25, s25, s24
	s_mul_hi_u32 s24, s14, s25
	s_mul_i32 s25, s24, s18
	s_sub_i32 s14, s14, s25
	s_add_i32 s26, s24, 1
	s_sub_i32 s25, s14, s18
	s_cmp_ge_u32 s14, s18
	s_cselect_b32 s24, s26, s24
	s_cselect_b32 s14, s25, s14
	s_add_i32 s25, s24, 1
	s_cmp_ge_u32 s14, s18
	s_cselect_b32 s14, s25, s24
	s_xor_b32 s14, s14, s19
	s_sub_i32 s14, s14, s19
	s_mul_i32 s17, s14, s17
	s_sub_i32 s15, s15, s17
	s_add_i32 s16, s16, s15
; #define PG8_STAGE(bufoff, gbase, voff) do { _Pragma("unroll") for (int _i = 0; _i < 2; ++_i) \
;         __builtin_amdgcn_global_load_lds((const unsigned*)((const char*)(gbase) + (voff)[_i]), (PG8_LAS unsigned*)(lds + (bufoff) + ldsw + _i * 8192), 16, 0, PG8_LOAD_AUX); } while (0)
; #define PG8_LDA(dst, b, h) do { _Pragma("unroll") for (int m = 0; m < 4; ++m) _Pragma("unroll") for (int k = 0; k < 2; ++k) dst[m][k] = *(const PG8_LAS bf16x8*)(lds + PG8_SA(b, h) + aoff + m * 2048 + k * 1024); } while (0)
; #define PG8_LDB(dst, b, h) do { _Pragma("unroll") for (int n = 0; n < 2; ++n) _Pragma("unroll") for (int k = 0; k < 2; ++k) dst[n][k] = *(const PG8_LAS bf16x8*)(lds + PG8_SB(b, h) + boff + n * 2048 + k * 1024); } while (0)
; #define PG8_WAIT_V(n) asm volatile("s_waitcnt vmcnt(" #n ")" ::: "memory")
; #define PG8_WAIT_L(n) asm volatile("s_waitcnt lgkmcnt(" #n ")" ::: "memory")
; #define PG8_BAR __builtin_amdgcn_s_barrier()
; #define PG8_SCHED __builtin_amdgcn_sched_barrier(0)
; template <class Epi, class Sched, bool ALIGN_EPI = false, bool SP2 = false>
; __device__ __forceinline__ void gemm_phase(PG8_LAS unsigned char* lds, const Gemm g, const Sched& S, const Epi& E) {
;     ...
;         const char* nA = has_next ? (const char*)g.A + (size_t)nxt.pm * tstepA + (size_t)nxt.pn * apn : cA; const char* nB = has_next ? (const char*)g.Bt + (size_t)nxt.pn * tstepB : cB;
;         for (int t = 0; t < nt; t += 2) {
;             const bool last = (t == nt - 2);
;             const char* a1 = cA + (size_t)(t + 1) * kstep;
;             const char* a2 = last ? nA : cA + (size_t)(t + 2) * kstep; const char* b2 = last ? nB : cB + (size_t)(t + 2) * kstep;
;             const char* a3 = a2 + kstep; const char* b3 = b2 + kstep;
;             if (last && has_next) S.a_ready(nxt);
;             if constexpr (SP2) {
;             PG8_LDB(B0, 0, 0); PG8_LDB(B1, 0, 1); PG8_SCHED; PG8_LDA(At, 0, 0); PG8_STAGE(PG8_SA(1, 1), a1 + hstepA, voffA);
;             PG8_WAIT_V(8); PG8_WAIT_L(0); PG8_BAR; PG8_MMA(0, 0, At, B0); PG8_MMA(0, 1, At, B1); PG8_BAR; PG8_SCHED;
;             PG8_LDA(At, 0, 1); PG8_STAGE(PG8_SB(0, 0), b2, voffB); PG8_STAGE(PG8_SB(0, 1), b2 + hstepB, voffB); PG8_STAGE(PG8_SA(0, 0), a2, voffA);
;             PG8_WAIT_V(8); PG8_WAIT_L(0); PG8_BAR; PG8_MMA(1, 0, At, B0); PG8_MMA(1, 1, At, B1); PG8_BAR; PG8_SCHED;
.LBB0_214:
	s_ashr_i32 s17, s16, 31
	s_lshl_b64 s[18:19], s[16:17], 19
	v_readlane_b32 s24, v239, 47
	v_readlane_b32 s25, v239, 48
	s_add_u32 s18, s24, s18
	s_addc_u32 s19, s25, s19
	s_and_b64 s[24:25], s[4:5], exec
	s_cselect_b32 s17, s19, s21
	s_cselect_b32 s24, s18, s20
	s_ashr_i32 s15, s14, 31
	s_lshl_b64 s[26:27], s[14:15], 19
	s_add_u32 s40, s64, s26
	s_addc_u32 s41, s65, s27
	s_and_b64 s[26:27], s[4:5], exec
	s_cselect_b32 s15, s41, s23
	s_cselect_b32 s25, s40, s22
	s_add_u32 s20, s20, 0x40080
	s_addc_u32 s21, s21, 0
	s_add_u32 s26, s22, 0x100
	s_addc_u32 s27, s23, 0
	s_mov_b32 s28, -2
	s_add_u32 s22, s20, 0xfffc0080
	s_addc_u32 s23, s21, -1
	s_cmp_eq_u32 s28, 12
	s_cselect_b32 s35, s17, s23
	s_cselect_b32 s34, s24, s22
	s_cselect_b32 s23, s15, s27
	s_cselect_b32 s22, s25, s26
	v_lshl_add_u64 v[226:227], s[20:21], 0, v[138:139]
	s_add_i32 m0, s42, 0xc000
	global_load_lds_dwordx4 v[226:227], off
	v_lshl_add_u64 v[226:227], s[20:21], 0, v[140:141]
	s_add_i32 m0, s42, 0xe000
	s_nop 0
	global_load_lds_dwordx4 v[226:227], off
	s_waitcnt vmcnt(8)
	s_waitcnt lgkmcnt(0)
	s_barrier
	s_setprio 1
	s_waitcnt lgkmcnt(0)
	v_mfma_f32_16x16x32_bf16 v[124:127], v[162:165], v[194:197], 0
	v_mfma_f32_16x16x32_bf16 v[120:123], v[170:173], v[194:197], 0
	v_mfma_f32_16x16x32_bf16 v[108:111], v[162:165], v[202:205], 0
	v_mfma_f32_16x16x32_bf16 v[104:107], v[170:173], v[202:205], 0
	v_mfma_f32_16x16x32_bf16 v[92:95], v[162:165], v[210:213], 0
	v_mfma_f32_16x16x32_bf16 v[88:91], v[170:173], v[210:213], 0
	v_mfma_f32_16x16x32_bf16 v[76:79], v[162:165], v[218:221], 0
	v_mfma_f32_16x16x32_bf16 v[72:75], v[170:173], v[218:221], 0
	v_mfma_f32_16x16x32_bf16 v[124:127], v[166:169], v[198:201], v[124:127]
	v_mfma_f32_16x16x32_bf16 v[120:123], v[174:177], v[198:201], v[120:123]
	v_mfma_f32_16x16x32_bf16 v[108:111], v[166:169], v[206:209], v[108:111]
	v_mfma_f32_16x16x32_bf16 v[104:107], v[174:177], v[206:209], v[104:107]
	v_mfma_f32_16x16x32_bf16 v[92:95], v[166:169], v[214:217], v[92:95]
	v_mfma_f32_16x16x32_bf16 v[88:91], v[174:177], v[214:217], v[88:91]
	v_mfma_f32_16x16x32_bf16 v[76:79], v[166:169], v[222:225], v[76:79]
	v_mfma_f32_16x16x32_bf16 v[72:75], v[174:177], v[222:225], v[72:75]
	s_setprio 0
	s_setprio 1
	v_mfma_f32_16x16x32_bf16 v[116:119], v[178:181], v[194:197], 0
	v_mfma_f32_16x16x32_bf16 v[112:115], v[186:189], v[194:197], 0
	v_mfma_f32_16x16x32_bf16 v[100:103], v[178:181], v[202:205], 0
	v_mfma_f32_16x16x32_bf16 v[96:99], v[186:189], v[202:205], 0
	v_mfma_f32_16x16x32_bf16 v[84:87], v[178:181], v[210:213], 0
	v_mfma_f32_16x16x32_bf16 v[80:83], v[186:189], v[210:213], 0
	v_mfma_f32_16x16x32_bf16 v[68:71], v[178:181], v[218:221], 0
	v_mfma_f32_16x16x32_bf16 v[64:67], v[186:189], v[218:221], 0
	v_mfma_f32_16x16x32_bf16 v[116:119], v[182:185], v[198:201], v[116:119]
	v_mfma_f32_16x16x32_bf16 v[112:115], v[190:193], v[198:201], v[112:115]
	v_mfma_f32_16x16x32_bf16 v[100:103], v[182:185], v[206:209], v[100:103]
	v_mfma_f32_16x16x32_bf16 v[96:99], v[190:193], v[206:209], v[96:99]
	v_mfma_f32_16x16x32_bf16 v[84:87], v[182:185], v[214:217], v[84:87]
	v_mfma_f32_16x16x32_bf16 v[80:83], v[190:193], v[214:217], v[80:83]
	v_mfma_f32_16x16x32_bf16 v[68:71], v[182:185], v[222:225], v[68:71]
	v_mfma_f32_16x16x32_bf16 v[64:67], v[190:193], v[222:225], v[64:67]
	s_setprio 0
	s_barrier
	s_add_i32 s29, s51, s33
	v_lshl_add_u64 v[226:227], s[22:23], 0, v[130:131]
	s_mov_b32 m0, s29
	ds_read_b128 v[194:197], v160 offset:16384
	ds_read_b128 v[198:201], v160 offset:17408
	ds_read_b128 v[202:205], v160 offset:18432
	ds_read_b128 v[206:209], v160 offset:19456
	ds_read_b128 v[210:213], v160 offset:20480
	ds_read_b128 v[214:217], v160 offset:21504
	ds_read_b128 v[218:221], v160 offset:22528
	ds_read_b128 v[222:225], v160 offset:23552
	global_load_lds_dwordx4 v[226:227], off
	s_add_i32 m0, s29, 0x2000
	s_add_u32 s30, s22, 0x10000
	v_lshl_add_u64 v[228:229], s[22:23], 0, v[134:135]
	s_addc_u32 s31, s23, 0
	s_add_i32 s29, s52, s33
	global_load_lds_dwordx4 v[228:229], off
	v_lshl_add_u64 v[230:231], s[30:31], 0, v[130:131]
	s_mov_b32 m0, s29
	v_lshl_add_u64 v[232:233], s[34:35], 0, v[132:133]
	global_load_lds_dwordx4 v[230:231], off
	v_lshl_add_u64 v[230:231], s[30:31], 0, v[134:135]
	s_add_i32 m0, s29, 0x2000
	s_nop 0
	global_load_lds_dwordx4 v[230:231], off
	v_lshl_add_u64 v[230:231], s[34:35], 0, v[128:129]
	s_mov_b32 m0, s42
	s_nop 0
	global_load_lds_dwordx4 v[230:231], off
	s_mov_b32 m0, s43
	s_nop 0
	global_load_lds_dwordx4 v[232:233], off
	s_waitcnt vmcnt(8)
	s_waitcnt lgkmcnt(0)
	s_barrier
	s_setprio 1
	s_waitcnt lgkmcnt(0)
	v_mfma_f32_16x16x32_bf16 v[60:63], v[162:165], v[194:197], 0
	v_mfma_f32_16x16x32_bf16 v[56:59], v[170:173], v[194:197], 0
	v_mfma_f32_16x16x32_bf16 v[44:47], v[162:165], v[202:205], 0
	v_mfma_f32_16x16x32_bf16 v[40:43], v[170:173], v[202:205], 0
	v_mfma_f32_16x16x32_bf16 v[28:31], v[162:165], v[210:213], 0
	v_mfma_f32_16x16x32_bf16 v[24:27], v[170:173], v[210:213], 0
	v_mfma_f32_16x16x32_bf16 v[12:15], v[162:165], v[218:221], 0
	v_mfma_f32_16x16x32_bf16 v[8:11], v[170:173], v[218:221], 0
	v_mfma_f32_16x16x32_bf16 v[60:63], v[166:169], v[198:201], v[60:63]
	v_mfma_f32_16x16x32_bf16 v[56:59], v[174:177], v[198:201], v[56:59]
	v_mfma_f32_16x16x32_bf16 v[44:47], v[166:169], v[206:209], v[44:47]
	v_mfma_f32_16x16x32_bf16 v[40:43], v[174:177], v[206:209], v[40:43]
	v_mfma_f32_16x16x32_bf16 v[28:31], v[166:169], v[214:217], v[28:31]
	v_mfma_f32_16x16x32_bf16 v[24:27], v[174:177], v[214:217], v[24:27]
	v_mfma_f32_16x16x32_bf16 v[12:15], v[166:169], v[222:225], v[12:15]
	v_mfma_f32_16x16x32_bf16 v[8:11], v[174:177], v[222:225], v[8:11]
	s_setprio 0
	s_setprio 1
	v_mfma_f32_16x16x32_bf16 v[52:55], v[178:181], v[194:197], 0
	v_mfma_f32_16x16x32_bf16 v[48:51], v[186:189], v[194:197], 0
	v_mfma_f32_16x16x32_bf16 v[36:39], v[178:181], v[202:205], 0
	v_mfma_f32_16x16x32_bf16 v[32:35], v[186:189], v[202:205], 0
	v_mfma_f32_16x16x32_bf16 v[20:23], v[178:181], v[210:213], 0
	v_mfma_f32_16x16x32_bf16 v[16:19], v[186:189], v[210:213], 0
	v_mfma_f32_16x16x32_bf16 v[4:7], v[178:181], v[218:221], 0
	v_mfma_f32_16x16x32_bf16 v[0:3], v[186:189], v[218:221], 0
	v_mfma_f32_16x16x32_bf16 v[52:55], v[182:185], v[198:201], v[52:55]
	v_mfma_f32_16x16x32_bf16 v[48:51], v[190:193], v[198:201], v[48:51]
	v_mfma_f32_16x16x32_bf16 v[36:39], v[182:185], v[206:209], v[36:39]
	v_mfma_f32_16x16x32_bf16 v[32:35], v[190:193], v[206:209], v[32:35]
	v_mfma_f32_16x16x32_bf16 v[20:23], v[182:185], v[214:217], v[20:23]
	v_mfma_f32_16x16x32_bf16 v[16:19], v[190:193], v[214:217], v[16:19]
	v_mfma_f32_16x16x32_bf16 v[4:7], v[182:185], v[222:225], v[4:7]
	v_mfma_f32_16x16x32_bf16 v[0:3], v[190:193], v[222:225], v[0:3]
	s_setprio 0
	s_barrier
	s_branch .Lkmid_P1

; #define PG8_STAGE(bufoff, gbase, voff) do { _Pragma("unroll") for (int _i = 0; _i < 2; ++_i) \
;         __builtin_amdgcn_global_load_lds((const unsigned*)((const char*)(gbase) + (voff)[_i]), (PG8_LAS unsigned*)(lds + (bufoff) + ldsw + _i * 8192), 16, 0, PG8_LOAD_AUX); } while (0)
; #define PG8_LDA(dst, b, h) do { _Pragma("unroll") for (int m = 0; m < 4; ++m) _Pragma("unroll") for (int k = 0; k < 2; ++k) dst[m][k] = *(const PG8_LAS bf16x8*)(lds + PG8_SA(b, h) + aoff + m * 2048 + k * 1024); } while (0)
; #define PG8_LDB(dst, b, h) do { _Pragma("unroll") for (int n = 0; n < 2; ++n) _Pragma("unroll") for (int k = 0; k < 2; ++k) dst[n][k] = *(const PG8_LAS bf16x8*)(lds + PG8_SB(b, h) + boff + n * 2048 + k * 1024); } while (0)
; #define PG8_SCHED __builtin_amdgcn_sched_barrier(0)
;     __host__ __device__ bool next(int i, Unit& u) const {
;         const long L = (long)i * G + c; if (L >= nwg) return false;
;         int wgid = (int)L; { const int q = nwg / NXCD, r = nwg % NXCD, xcd = wgid % NXCD, off = wgid / NXCD; wgid = (xcd < r ? xcd * (q + 1) : r * (q + 1) + (xcd - r) * q) + off; }
;         const int nig = WGM * nN, gid = wgid / nig, fm = gid * WGM, gsz = (nM - fm) < WGM ? (nM - fm) : WGM;
;         u.pm = fm + ((wgid % nig) % gsz); u.pn = (wgid % nig) / gsz; return true;
; template <class Epi, class Sched, bool ALIGN_EPI = false, bool SP2 = false>
; __device__ __forceinline__ void gemm_phase(PG8_LAS unsigned char* lds, const Gemm g, const Sched& S, const Epi& E) {
;     ...
;         const bool has_next = S.next(ui + 1, nxt);
;         const char* nA = has_next ? (const char*)g.A + (size_t)nxt.pm * tstepA + (size_t)nxt.pn * apn : cA; const char* nB = has_next ? (const char*)g.Bt + (size_t)nxt.pn * tstepB : cB;
;         for (int t = 0; t < nt; t += 2) {
;             const bool last = (t == nt - 2);
;             const char* a1 = cA + (size_t)(t + 1) * kstep;
;             const char* a2 = last ? nA : cA + (size_t)(t + 2) * kstep; const char* b2 = last ? nB : cB + (size_t)(t + 2) * kstep;
;             const char* a3 = a2 + kstep; const char* b3 = b2 + kstep;
;             if (last && has_next) S.a_ready(nxt);
;             if constexpr (SP2) {
;             PG8_LDB(B0, 0, 0); PG8_LDB(B1, 0, 1); PG8_SCHED; PG8_LDA(At, 0, 0); PG8_STAGE(PG8_SA(1, 1), a1 + hstepA, voffA);
.LBB0_366:
	ds_read_b128 v[162:165], v159
	ds_read_b128 v[166:169], v159 offset:1024
	ds_read_b128 v[170:173], v159 offset:2048
	ds_read_b128 v[174:177], v159 offset:3072
	ds_read_b128 v[178:181], v160
	ds_read_b128 v[182:185], v160 offset:1024
	ds_read_b128 v[186:189], v160 offset:2048
	ds_read_b128 v[190:193], v160 offset:3072
	ds_read_b128 v[194:197], v161
	ds_read_b128 v[198:201], v161 offset:1024
	ds_read_b128 v[202:205], v161 offset:2048
	ds_read_b128 v[206:209], v161 offset:3072
	ds_read_b128 v[210:213], v161 offset:4096
	ds_read_b128 v[214:217], v161 offset:5120
	ds_read_b128 v[218:221], v161 offset:6144
	ds_read_b128 v[222:225], v161 offset:7168
	s_add_i32 s48, s48, 1
	s_mul_i32 s4, s48, s51
	s_mul_hi_u32 s5, s48, s52
	s_add_i32 s5, s5, s4
	s_mul_i32 s4, s48, s52
	v_readlane_b32 s15, v239, 0
	s_add_u32 s18, s4, s15
	s_addc_u32 s19, s5, s42
	v_cmp_gt_i64_e32 vcc, s[18:19], v[144:145]
	v_cmp_lt_i64_e64 s[4:5], s[18:19], v[142:143]
	s_cbranch_vccnz .LBB0_368
	s_ashr_i32 s14, s18, 31
	s_lshr_b32 s14, s14, 29
	s_add_i32 s14, s18, s14
	s_ashr_i32 s15, s14, 3
	s_and_b32 s14, s14, -8
	s_sub_i32 s14, s18, s14
	s_cmp_lt_i32 s14, 0
	s_cselect_b32 s16, s43, 0x120
	s_mul_i32 s14, s14, s16
	s_add_i32 s14, s14, s15
	s_mul_hi_i32 s15, s14, 0x38e38e39
	s_lshr_b32 s16, s15, 31
	s_ashr_i32 s15, s15, 5
	s_add_i32 s15, s15, s16
	s_lshl_b32 s16, s15, 2
	s_sub_i32 s17, 64, s16
	s_min_i32 s17, s17, 4
	s_abs_i32 s18, s17
	v_cvt_f32_u32_e32 v0, s18
	s_sub_i32 s24, 0, s18
	s_mulk_i32 s15, 0x90
	s_sub_i32 s15, s14, s15
	v_rcp_iflag_f32_e32 v0, v0
	s_abs_i32 s14, s15
	s_xor_b32 s19, s15, s17
	s_ashr_i32 s19, s19, 31
	v_mul_f32_e32 v0, 0x4f7ffffe, v0
	v_cvt_u32_f32_e32 v0, v0
	s_nop 0
	v_readfirstlane_b32 s25, v0
	s_mul_i32 s24, s24, s25
	s_mul_hi_u32 s24, s25, s24
	s_add_i32 s25, s25, s24
	s_mul_hi_u32 s24, s14, s25
	s_mul_i32 s25, s24, s18
	s_sub_i32 s14, s14, s25
	s_add_i32 s26, s24, 1
	s_sub_i32 s25, s14, s18
	s_cmp_ge_u32 s14, s18
	s_cselect_b32 s24, s26, s24
	s_cselect_b32 s14, s25, s14
	s_add_i32 s25, s24, 1
	s_cmp_ge_u32 s14, s18
	s_cselect_b32 s14, s25, s24
	s_xor_b32 s14, s14, s19
	s_sub_i32 s14, s14, s19
	s_mul_i32 s17, s14, s17
	s_sub_i32 s15, s15, s17
	s_add_i32 s16, s16, s15
; #define PG8_STAGE(bufoff, gbase, voff) do { _Pragma("unroll") for (int _i = 0; _i < 2; ++_i) \
;         __builtin_amdgcn_global_load_lds((const unsigned*)((const char*)(gbase) + (voff)[_i]), (PG8_LAS unsigned*)(lds + (bufoff) + ldsw + _i * 8192), 16, 0, PG8_LOAD_AUX); } while (0)
; #define PG8_LDA(dst, b, h) do { _Pragma("unroll") for (int m = 0; m < 4; ++m) _Pragma("unroll") for (int k = 0; k < 2; ++k) dst[m][k] = *(const PG8_LAS bf16x8*)(lds + PG8_SA(b, h) + aoff + m * 2048 + k * 1024); } while (0)
; #define PG8_LDB(dst, b, h) do { _Pragma("unroll") for (int n = 0; n < 2; ++n) _Pragma("unroll") for (int k = 0; k < 2; ++k) dst[n][k] = *(const PG8_LAS bf16x8*)(lds + PG8_SB(b, h) + boff + n * 2048 + k * 1024); } while (0)
; #define PG8_WAIT_V(n) asm volatile("s_waitcnt vmcnt(" #n ")" ::: "memory")
; #define PG8_WAIT_L(n) asm volatile("s_waitcnt lgkmcnt(" #n ")" ::: "memory")
; #define PG8_BAR __builtin_amdgcn_s_barrier()
; #define PG8_SCHED __builtin_amdgcn_sched_barrier(0)
; template <class Epi, class Sched, bool ALIGN_EPI = false, bool SP2 = false>
; __device__ __forceinline__ void gemm_phase(PG8_LAS unsigned char* lds, const Gemm g, const Sched& S, const Epi& E) {
;     ...
;         const char* nA = has_next ? (const char*)g.A + (size_t)nxt.pm * tstepA + (size_t)nxt.pn * apn : cA; const char* nB = has_next ? (const char*)g.Bt + (size_t)nxt.pn * tstepB : cB;
;         for (int t = 0; t < nt; t += 2) {
;             const bool last = (t == nt - 2);
;             const char* a1 = cA + (size_t)(t + 1) * kstep;
;             const char* a2 = last ? nA : cA + (size_t)(t + 2) * kstep; const char* b2 = last ? nB : cB + (size_t)(t + 2) * kstep;
;             const char* a3 = a2 + kstep; const char* b3 = b2 + kstep;
;             if (last && has_next) S.a_ready(nxt);
;             if constexpr (SP2) {
;             PG8_LDB(B0, 0, 0); PG8_LDB(B1, 0, 1); PG8_SCHED; PG8_LDA(At, 0, 0); PG8_STAGE(PG8_SA(1, 1), a1 + hstepA, voffA);
;             PG8_WAIT_V(8); PG8_WAIT_L(0); PG8_BAR; PG8_MMA(0, 0, At, B0); PG8_MMA(0, 1, At, B1); PG8_BAR; PG8_SCHED;
;             PG8_LDA(At, 0, 1); PG8_STAGE(PG8_SB(0, 0), b2, voffB); PG8_STAGE(PG8_SB(0, 1), b2 + hstepB, voffB); PG8_STAGE(PG8_SA(0, 0), a2, voffA);
;             PG8_WAIT_V(8); PG8_WAIT_L(0); PG8_BAR; PG8_MMA(1, 0, At, B0); PG8_MMA(1, 1, At, B1); PG8_BAR; PG8_SCHED;
.LBB0_368:
	s_ashr_i32 s17, s16, 31
	s_lshl_b64 s[18:19], s[16:17], 19
	s_add_u32 s18, s33, s18
	s_addc_u32 s19, s36, s19
	s_and_b64 s[24:25], s[4:5], exec
	s_cselect_b32 s17, s19, s21
	s_cselect_b32 s24, s18, s20
	s_ashr_i32 s15, s14, 31
	s_lshl_b64 s[26:27], s[14:15], 19
	s_add_u32 s40, s64, s26
	s_addc_u32 s41, s65, s27
	s_and_b64 s[26:27], s[4:5], exec
	s_cselect_b32 s15, s41, s23
	s_cselect_b32 s25, s40, s22
	s_add_u32 s20, s20, 0x40080
	s_addc_u32 s21, s21, 0
	s_add_u32 s26, s22, 0x100
	s_addc_u32 s27, s23, 0
	s_mov_b32 s28, -2
	s_add_u32 s22, s20, 0xfffc0080
	s_addc_u32 s23, s21, -1
	s_cmp_eq_u32 s28, 12
	s_cselect_b32 s35, s17, s23
	s_cselect_b32 s34, s24, s22
	s_cselect_b32 s23, s15, s27
	s_cselect_b32 s22, s25, s26
	v_lshl_add_u64 v[226:227], s[20:21], 0, v[138:139]
	s_add_i32 m0, s44, 0xc000
	global_load_lds_dwordx4 v[226:227], off
	v_lshl_add_u64 v[226:227], s[20:21], 0, v[140:141]
	s_add_i32 m0, s44, 0xe000
	s_nop 0
	global_load_lds_dwordx4 v[226:227], off
	s_waitcnt vmcnt(8)
	s_waitcnt lgkmcnt(0)
	s_barrier
	s_setprio 1
	s_waitcnt lgkmcnt(0)
	v_mfma_f32_16x16x32_bf16 v[124:127], v[162:165], v[194:197], 0
	v_mfma_f32_16x16x32_bf16 v[120:123], v[170:173], v[194:197], 0
	v_mfma_f32_16x16x32_bf16 v[108:111], v[162:165], v[202:205], 0
	v_mfma_f32_16x16x32_bf16 v[104:107], v[170:173], v[202:205], 0
	v_mfma_f32_16x16x32_bf16 v[92:95], v[162:165], v[210:213], 0
	v_mfma_f32_16x16x32_bf16 v[88:91], v[170:173], v[210:213], 0
	v_mfma_f32_16x16x32_bf16 v[76:79], v[162:165], v[218:221], 0
	v_mfma_f32_16x16x32_bf16 v[72:75], v[170:173], v[218:221], 0
	v_mfma_f32_16x16x32_bf16 v[124:127], v[166:169], v[198:201], v[124:127]
	v_mfma_f32_16x16x32_bf16 v[120:123], v[174:177], v[198:201], v[120:123]
	v_mfma_f32_16x16x32_bf16 v[108:111], v[166:169], v[206:209], v[108:111]
	v_mfma_f32_16x16x32_bf16 v[104:107], v[174:177], v[206:209], v[104:107]
	v_mfma_f32_16x16x32_bf16 v[92:95], v[166:169], v[214:217], v[92:95]
	v_mfma_f32_16x16x32_bf16 v[88:91], v[174:177], v[214:217], v[88:91]
	v_mfma_f32_16x16x32_bf16 v[76:79], v[166:169], v[222:225], v[76:79]
	v_mfma_f32_16x16x32_bf16 v[72:75], v[174:177], v[222:225], v[72:75]
	s_setprio 0
	s_setprio 1
	v_mfma_f32_16x16x32_bf16 v[116:119], v[178:181], v[194:197], 0
	v_mfma_f32_16x16x32_bf16 v[112:115], v[186:189], v[194:197], 0
	v_mfma_f32_16x16x32_bf16 v[100:103], v[178:181], v[202:205], 0
	v_mfma_f32_16x16x32_bf16 v[96:99], v[186:189], v[202:205], 0
	v_mfma_f32_16x16x32_bf16 v[84:87], v[178:181], v[210:213], 0
	v_mfma_f32_16x16x32_bf16 v[80:83], v[186:189], v[210:213], 0
	v_mfma_f32_16x16x32_bf16 v[68:71], v[178:181], v[218:221], 0
	v_mfma_f32_16x16x32_bf16 v[64:67], v[186:189], v[218:221], 0
	v_mfma_f32_16x16x32_bf16 v[116:119], v[182:185], v[198:201], v[116:119]
	v_mfma_f32_16x16x32_bf16 v[112:115], v[190:193], v[198:201], v[112:115]
	v_mfma_f32_16x16x32_bf16 v[100:103], v[182:185], v[206:209], v[100:103]
	v_mfma_f32_16x16x32_bf16 v[96:99], v[190:193], v[206:209], v[96:99]
	v_mfma_f32_16x16x32_bf16 v[84:87], v[182:185], v[214:217], v[84:87]
	v_mfma_f32_16x16x32_bf16 v[80:83], v[190:193], v[214:217], v[80:83]
	v_mfma_f32_16x16x32_bf16 v[68:71], v[182:185], v[222:225], v[68:71]
	v_mfma_f32_16x16x32_bf16 v[64:67], v[190:193], v[222:225], v[64:67]
	s_setprio 0
	s_barrier
	s_add_i32 s29, s53, s37
	v_lshl_add_u64 v[226:227], s[22:23], 0, v[132:133]
	s_mov_b32 m0, s29
	ds_read_b128 v[194:197], v161 offset:16384
	ds_read_b128 v[198:201], v161 offset:17408
	ds_read_b128 v[202:205], v161 offset:18432
	ds_read_b128 v[206:209], v161 offset:19456
	ds_read_b128 v[210:213], v161 offset:20480
	ds_read_b128 v[214:217], v161 offset:21504
	ds_read_b128 v[218:221], v161 offset:22528
	ds_read_b128 v[222:225], v161 offset:23552
	global_load_lds_dwordx4 v[226:227], off
	s_add_i32 m0, s29, 0x2000
	s_add_u32 s30, s22, 0x10000
	v_lshl_add_u64 v[228:229], s[22:23], 0, v[128:129]
	s_addc_u32 s31, s23, 0
	s_add_i32 s29, s54, s37
	global_load_lds_dwordx4 v[228:229], off
	v_lshl_add_u64 v[230:231], s[30:31], 0, v[132:133]
	s_mov_b32 m0, s29
	v_lshl_add_u64 v[232:233], s[34:35], 0, v[130:131]
	global_load_lds_dwordx4 v[230:231], off
	v_lshl_add_u64 v[230:231], s[30:31], 0, v[128:129]
	s_add_i32 m0, s29, 0x2000
	s_nop 0
	global_load_lds_dwordx4 v[230:231], off
	v_lshl_add_u64 v[230:231], s[34:35], 0, v[134:135]
	s_mov_b32 m0, s44
	s_nop 0
	global_load_lds_dwordx4 v[230:231], off
	s_mov_b32 m0, s45
	s_nop 0
	global_load_lds_dwordx4 v[232:233], off
	s_waitcnt vmcnt(8)
	s_waitcnt lgkmcnt(0)
	s_barrier
	s_setprio 1
	s_waitcnt lgkmcnt(0)
	v_mfma_f32_16x16x32_bf16 v[60:63], v[162:165], v[194:197], 0
	v_mfma_f32_16x16x32_bf16 v[56:59], v[170:173], v[194:197], 0
	v_mfma_f32_16x16x32_bf16 v[44:47], v[162:165], v[202:205], 0
	v_mfma_f32_16x16x32_bf16 v[40:43], v[170:173], v[202:205], 0
	v_mfma_f32_16x16x32_bf16 v[28:31], v[162:165], v[210:213], 0
	v_mfma_f32_16x16x32_bf16 v[24:27], v[170:173], v[210:213], 0
	v_mfma_f32_16x16x32_bf16 v[12:15], v[162:165], v[218:221], 0
	v_mfma_f32_16x16x32_bf16 v[8:11], v[170:173], v[218:221], 0
	v_mfma_f32_16x16x32_bf16 v[60:63], v[166:169], v[198:201], v[60:63]
	v_mfma_f32_16x16x32_bf16 v[56:59], v[174:177], v[198:201], v[56:59]
	v_mfma_f32_16x16x32_bf16 v[44:47], v[166:169], v[206:209], v[44:47]
	v_mfma_f32_16x16x32_bf16 v[40:43], v[174:177], v[206:209], v[40:43]
	v_mfma_f32_16x16x32_bf16 v[28:31], v[166:169], v[214:217], v[28:31]
	v_mfma_f32_16x16x32_bf16 v[24:27], v[174:177], v[214:217], v[24:27]
	v_mfma_f32_16x16x32_bf16 v[12:15], v[166:169], v[222:225], v[12:15]
	v_mfma_f32_16x16x32_bf16 v[8:11], v[174:177], v[222:225], v[8:11]
	s_setprio 0
	s_setprio 1
	v_mfma_f32_16x16x32_bf16 v[52:55], v[178:181], v[194:197], 0
	v_mfma_f32_16x16x32_bf16 v[48:51], v[186:189], v[194:197], 0
	v_mfma_f32_16x16x32_bf16 v[36:39], v[178:181], v[202:205], 0
	v_mfma_f32_16x16x32_bf16 v[32:35], v[186:189], v[202:205], 0
	v_mfma_f32_16x16x32_bf16 v[20:23], v[178:181], v[210:213], 0
	v_mfma_f32_16x16x32_bf16 v[16:19], v[186:189], v[210:213], 0
	v_mfma_f32_16x16x32_bf16 v[4:7], v[178:181], v[218:221], 0
	v_mfma_f32_16x16x32_bf16 v[0:3], v[186:189], v[218:221], 0
	v_mfma_f32_16x16x32_bf16 v[52:55], v[182:185], v[198:201], v[52:55]
	v_mfma_f32_16x16x32_bf16 v[48:51], v[190:193], v[198:201], v[48:51]
	v_mfma_f32_16x16x32_bf16 v[36:39], v[182:185], v[206:209], v[36:39]
	v_mfma_f32_16x16x32_bf16 v[32:35], v[190:193], v[206:209], v[32:35]
	v_mfma_f32_16x16x32_bf16 v[20:23], v[182:185], v[214:217], v[20:23]
	v_mfma_f32_16x16x32_bf16 v[16:19], v[190:193], v[214:217], v[16:19]
	v_mfma_f32_16x16x32_bf16 v[4:7], v[182:185], v[222:225], v[4:7]
	v_mfma_f32_16x16x32_bf16 v[0:3], v[190:193], v[222:225], v[0:3]
	s_setprio 0
	s_barrier
	s_branch .Lkmid_P3

; #define PG8_STAGE(bufoff, gbase, voff) do { _Pragma("unroll") for (int _i = 0; _i < 2; ++_i) \
;         __builtin_amdgcn_global_load_lds((const unsigned*)((const char*)(gbase) + (voff)[_i]), (PG8_LAS unsigned*)(lds + (bufoff) + ldsw + _i * 8192), 16, 0, PG8_LOAD_AUX); } while (0)
; #define PG8_LDA(dst, b, h) do { _Pragma("unroll") for (int m = 0; m < 4; ++m) _Pragma("unroll") for (int k = 0; k < 2; ++k) dst[m][k] = *(const PG8_LAS bf16x8*)(lds + PG8_SA(b, h) + aoff + m * 2048 + k * 1024); } while (0)
; #define PG8_LDB(dst, b, h) do { _Pragma("unroll") for (int n = 0; n < 2; ++n) _Pragma("unroll") for (int k = 0; k < 2; ++k) dst[n][k] = *(const PG8_LAS bf16x8*)(lds + PG8_SB(b, h) + boff + n * 2048 + k * 1024); } while (0)
; #define PG8_SCHED __builtin_amdgcn_sched_barrier(0)
;     __host__ __device__ bool next(int i, Unit& u) const {
;         const long L = (long)i * G + c; if (L >= nwg) return false;
;         int wgid = (int)L; { const int q = nwg / NXCD, r = nwg % NXCD, xcd = wgid % NXCD, off = wgid / NXCD; wgid = (xcd < r ? xcd * (q + 1) : r * (q + 1) + (xcd - r) * q) + off; }
;         const int nig = WGM * nN, gid = wgid / nig, fm = gid * WGM, gsz = (nM - fm) < WGM ? (nM - fm) : WGM;
;         u.pm = fm + ((wgid % nig) % gsz); u.pn = (wgid % nig) / gsz; return true;
; template <class Epi, class Sched, bool ALIGN_EPI = false, bool SP2 = false>
; __device__ __forceinline__ void gemm_phase(PG8_LAS unsigned char* lds, const Gemm g, const Sched& S, const Epi& E) {
;     ...
;         const bool has_next = S.next(ui + 1, nxt);
;         const char* nA = has_next ? (const char*)g.A + (size_t)nxt.pm * tstepA + (size_t)nxt.pn * apn : cA; const char* nB = has_next ? (const char*)g.Bt + (size_t)nxt.pn * tstepB : cB;
;         for (int t = 0; t < nt; t += 2) {
;             const bool last = (t == nt - 2);
;             const char* a1 = cA + (size_t)(t + 1) * kstep;
;             const char* a2 = last ? nA : cA + (size_t)(t + 2) * kstep; const char* b2 = last ? nB : cB + (size_t)(t + 2) * kstep;
;             const char* a3 = a2 + kstep; const char* b3 = b2 + kstep;
;             if (last && has_next) S.a_ready(nxt);
;             if constexpr (SP2) {
;             PG8_LDB(B0, 0, 0); PG8_LDB(B1, 0, 1); PG8_SCHED; PG8_LDA(At, 0, 0); PG8_STAGE(PG8_SA(1, 1), a1 + hstepA, voffA);
.LBB0_578:
	ds_read_b128 v[146:149], v157
	ds_read_b128 v[162:165], v157 offset:1024
	ds_read_b128 v[166:169], v157 offset:2048
	ds_read_b128 v[170:173], v157 offset:3072
	ds_read_b128 v[174:177], v158
	ds_read_b128 v[178:181], v158 offset:1024
	ds_read_b128 v[182:185], v158 offset:2048
	ds_read_b128 v[186:189], v158 offset:3072
	ds_read_b128 v[190:193], v159
	ds_read_b128 v[194:197], v159 offset:1024
	ds_read_b128 v[198:201], v159 offset:2048
	ds_read_b128 v[202:205], v159 offset:3072
	ds_read_b128 v[206:209], v159 offset:4096
	ds_read_b128 v[210:213], v159 offset:5120
	ds_read_b128 v[214:217], v159 offset:6144
	ds_read_b128 v[218:221], v159 offset:7168
	s_add_i32 s62, s62, 1
	s_mul_i32 s6, s62, s53
	s_mul_hi_u32 s7, s62, s59
	s_add_i32 s7, s7, s6
	s_mul_i32 s6, s62, s59
	v_readlane_b32 s19, v239, 0
	s_add_u32 s22, s6, s19
	s_addc_u32 s23, s7, s54
	v_cmp_gt_i64_e32 vcc, s[22:23], v[144:145]
	v_cmp_lt_i64_e64 s[6:7], s[22:23], v[142:143]
	s_cbranch_vccnz .LBB0_584
	s_ashr_i32 s18, s22, 31
	s_lshr_b32 s18, s18, 29
	s_add_i32 s23, s22, s18
	s_and_b32 s18, s23, -8
	s_sub_i32 s22, s22, s18
	s_cmp_gt_i32 s22, -1
	s_mov_b64 s[18:19], -1
	s_cbranch_scc0 .LBB0_581
	s_lshl_b32 s24, s22, 6
	s_mov_b64 s[18:19], 0

; #define PG8_STAGE(bufoff, gbase, voff) do { _Pragma("unroll") for (int _i = 0; _i < 2; ++_i) \
;         __builtin_amdgcn_global_load_lds((const unsigned*)((const char*)(gbase) + (voff)[_i]), (PG8_LAS unsigned*)(lds + (bufoff) + ldsw + _i * 8192), 16, 0, PG8_LOAD_AUX); } while (0)
; #define PG8_LDA(dst, b, h) do { _Pragma("unroll") for (int m = 0; m < 4; ++m) _Pragma("unroll") for (int k = 0; k < 2; ++k) dst[m][k] = *(const PG8_LAS bf16x8*)(lds + PG8_SA(b, h) + aoff + m * 2048 + k * 1024); } while (0)
; #define PG8_LDB(dst, b, h) do { _Pragma("unroll") for (int n = 0; n < 2; ++n) _Pragma("unroll") for (int k = 0; k < 2; ++k) dst[n][k] = *(const PG8_LAS bf16x8*)(lds + PG8_SB(b, h) + boff + n * 2048 + k * 1024); } while (0)
; #define PG8_WAIT_V(n) asm volatile("s_waitcnt vmcnt(" #n ")" ::: "memory")
; #define PG8_WAIT_L(n) asm volatile("s_waitcnt lgkmcnt(" #n ")" ::: "memory")
; #define PG8_BAR __builtin_amdgcn_s_barrier()
; #define PG8_SCHED __builtin_amdgcn_sched_barrier(0)
; template <class Epi, class Sched, bool ALIGN_EPI = false, bool SP2 = false>
; __device__ __forceinline__ void gemm_phase(PG8_LAS unsigned char* lds, const Gemm g, const Sched& S, const Epi& E) {
;     ...
;         const char* nA = has_next ? (const char*)g.A + (size_t)nxt.pm * tstepA + (size_t)nxt.pn * apn : cA; const char* nB = has_next ? (const char*)g.Bt + (size_t)nxt.pn * tstepB : cB;
;         for (int t = 0; t < nt; t += 2) {
;             const bool last = (t == nt - 2);
;             const char* a1 = cA + (size_t)(t + 1) * kstep;
;             const char* a2 = last ? nA : cA + (size_t)(t + 2) * kstep; const char* b2 = last ? nB : cB + (size_t)(t + 2) * kstep;
;             const char* a3 = a2 + kstep; const char* b3 = b2 + kstep;
;             if (last && has_next) S.a_ready(nxt);
;             if constexpr (SP2) {
;             PG8_LDB(B0, 0, 0); PG8_LDB(B1, 0, 1); PG8_SCHED; PG8_LDA(At, 0, 0); PG8_STAGE(PG8_SA(1, 1), a1 + hstepA, voffA);
;             PG8_WAIT_V(8); PG8_WAIT_L(0); PG8_BAR; PG8_MMA(0, 0, At, B0); PG8_MMA(0, 1, At, B1); PG8_BAR; PG8_SCHED;
;             PG8_LDA(At, 0, 1); PG8_STAGE(PG8_SB(0, 0), b2, voffB); PG8_STAGE(PG8_SB(0, 1), b2 + hstepB, voffB); PG8_STAGE(PG8_SA(0, 0), a2, voffA);
;             PG8_WAIT_V(8); PG8_WAIT_L(0); PG8_BAR; PG8_MMA(1, 0, At, B0); PG8_MMA(1, 1, At, B1); PG8_BAR; PG8_SCHED;
.LBB0_584:
	s_ashr_i32 s41, s40, 31
	s_lshl_b64 s[22:23], s[40:41], 19
	v_readlane_b32 s24, v239, 47
	v_readlane_b32 s25, v239, 48
	s_add_u32 s42, s24, s22
	s_addc_u32 s43, s25, s23
	s_and_b64 s[22:23], s[6:7], exec
	s_cselect_b32 s24, s43, s1
	s_cselect_b32 s25, s42, s0
	s_ashr_i32 s19, s18, 31
	s_lshl_b64 s[22:23], s[18:19], 19
	v_readlane_b32 s26, v239, 34
	v_readlane_b32 s27, v239, 35
	s_add_u32 s46, s26, s22
	s_addc_u32 s47, s27, s23
	s_and_b64 s[22:23], s[6:7], exec
	s_cselect_b32 s19, s47, s21
	s_cselect_b32 s26, s46, s20
	s_add_u32 s0, s0, 0x40080
	s_addc_u32 s1, s1, 0
	s_add_u32 s27, s20, 0x100
	s_addc_u32 s28, s21, 0
	s_mov_b32 s29, -2
	s_waitcnt lgkmcnt(0)
	s_add_u32 s20, s0, 0xfffc0080
	s_addc_u32 s21, s1, -1
	s_cmp_eq_u32 s29, 12
	s_cselect_b32 s23, s24, s21
	s_cselect_b32 s22, s25, s20
	s_cselect_b32 s21, s19, s28
	s_cselect_b32 s20, s26, s27
	v_lshl_add_u64 v[222:223], s[0:1], 0, v[138:139]
	s_add_i32 m0, s35, 0xc000
	global_load_lds_dwordx4 v[222:223], off
	v_lshl_add_u64 v[222:223], s[0:1], 0, v[140:141]
	s_add_i32 m0, s35, 0xe000
	s_nop 0
	global_load_lds_dwordx4 v[222:223], off
	s_waitcnt vmcnt(8)
	s_waitcnt lgkmcnt(0)
	s_barrier
	s_setprio 1
	s_waitcnt lgkmcnt(0)
	v_mfma_f32_16x16x32_bf16 v[124:127], v[146:149], v[190:193], 0
	v_mfma_f32_16x16x32_bf16 v[120:123], v[166:169], v[190:193], 0
	v_mfma_f32_16x16x32_bf16 v[108:111], v[146:149], v[198:201], 0
	v_mfma_f32_16x16x32_bf16 v[104:107], v[166:169], v[198:201], 0
	v_mfma_f32_16x16x32_bf16 v[92:95], v[146:149], v[206:209], 0
	v_mfma_f32_16x16x32_bf16 v[88:91], v[166:169], v[206:209], 0
	v_mfma_f32_16x16x32_bf16 v[76:79], v[146:149], v[214:217], 0
	v_mfma_f32_16x16x32_bf16 v[72:75], v[166:169], v[214:217], 0
	v_mfma_f32_16x16x32_bf16 v[124:127], v[162:165], v[194:197], v[124:127]
	v_mfma_f32_16x16x32_bf16 v[120:123], v[170:173], v[194:197], v[120:123]
	v_mfma_f32_16x16x32_bf16 v[108:111], v[162:165], v[202:205], v[108:111]
	v_mfma_f32_16x16x32_bf16 v[104:107], v[170:173], v[202:205], v[104:107]
	v_mfma_f32_16x16x32_bf16 v[92:95], v[162:165], v[210:213], v[92:95]
	v_mfma_f32_16x16x32_bf16 v[88:91], v[170:173], v[210:213], v[88:91]
	v_mfma_f32_16x16x32_bf16 v[76:79], v[162:165], v[218:221], v[76:79]
	v_mfma_f32_16x16x32_bf16 v[72:75], v[170:173], v[218:221], v[72:75]
	s_setprio 0
	s_setprio 1
	v_mfma_f32_16x16x32_bf16 v[116:119], v[174:177], v[190:193], 0
	v_mfma_f32_16x16x32_bf16 v[112:115], v[182:185], v[190:193], 0
	v_mfma_f32_16x16x32_bf16 v[100:103], v[174:177], v[198:201], 0
	v_mfma_f32_16x16x32_bf16 v[96:99], v[182:185], v[198:201], 0
	v_mfma_f32_16x16x32_bf16 v[84:87], v[174:177], v[206:209], 0
	v_mfma_f32_16x16x32_bf16 v[80:83], v[182:185], v[206:209], 0
	v_mfma_f32_16x16x32_bf16 v[68:71], v[174:177], v[214:217], 0
	v_mfma_f32_16x16x32_bf16 v[64:67], v[182:185], v[214:217], 0
	v_mfma_f32_16x16x32_bf16 v[116:119], v[178:181], v[194:197], v[116:119]
	v_mfma_f32_16x16x32_bf16 v[112:115], v[186:189], v[194:197], v[112:115]
	v_mfma_f32_16x16x32_bf16 v[100:103], v[178:181], v[202:205], v[100:103]
	v_mfma_f32_16x16x32_bf16 v[96:99], v[186:189], v[202:205], v[96:99]
	v_mfma_f32_16x16x32_bf16 v[84:87], v[178:181], v[210:213], v[84:87]
	v_mfma_f32_16x16x32_bf16 v[80:83], v[186:189], v[210:213], v[80:83]
	v_mfma_f32_16x16x32_bf16 v[68:71], v[178:181], v[218:221], v[68:71]
	v_mfma_f32_16x16x32_bf16 v[64:67], v[186:189], v[218:221], v[64:67]
	s_setprio 0
	s_barrier
	s_add_i32 s30, s60, s34
	v_lshl_add_u64 v[222:223], s[20:21], 0, v[130:131]
	s_mov_b32 m0, s30
	ds_read_b128 v[190:193], v159 offset:16384
	ds_read_b128 v[194:197], v159 offset:17408
	ds_read_b128 v[198:201], v159 offset:18432
	ds_read_b128 v[202:205], v159 offset:19456
	ds_read_b128 v[206:209], v159 offset:20480
	ds_read_b128 v[210:213], v159 offset:21504
	ds_read_b128 v[214:217], v159 offset:22528
	ds_read_b128 v[218:221], v159 offset:23552
	global_load_lds_dwordx4 v[222:223], off
	s_add_i32 m0, s30, 0x2000
	s_add_u32 s30, s20, 0x10000
	v_lshl_add_u64 v[224:225], s[20:21], 0, v[134:135]
	s_addc_u32 s31, s21, 0
	s_add_i32 s33, s61, s34
	global_load_lds_dwordx4 v[224:225], off
	v_lshl_add_u64 v[226:227], s[30:31], 0, v[130:131]
	s_mov_b32 m0, s33
	v_lshl_add_u64 v[228:229], s[22:23], 0, v[132:133]
	global_load_lds_dwordx4 v[226:227], off
	v_lshl_add_u64 v[226:227], s[30:31], 0, v[134:135]
	s_add_i32 m0, s33, 0x2000
	s_nop 0
	global_load_lds_dwordx4 v[226:227], off
	v_lshl_add_u64 v[226:227], s[22:23], 0, v[128:129]
	s_mov_b32 m0, s35
	s_nop 0
	global_load_lds_dwordx4 v[226:227], off
	s_mov_b32 m0, s49
	s_nop 0
	global_load_lds_dwordx4 v[228:229], off
	s_waitcnt vmcnt(8)
	s_waitcnt lgkmcnt(0)
	s_barrier
	s_setprio 1
	s_waitcnt lgkmcnt(0)
	v_mfma_f32_16x16x32_bf16 v[60:63], v[146:149], v[190:193], 0
	v_mfma_f32_16x16x32_bf16 v[56:59], v[166:169], v[190:193], 0
	v_mfma_f32_16x16x32_bf16 v[44:47], v[146:149], v[198:201], 0
	v_mfma_f32_16x16x32_bf16 v[40:43], v[166:169], v[198:201], 0
	v_mfma_f32_16x16x32_bf16 v[28:31], v[146:149], v[206:209], 0
	v_mfma_f32_16x16x32_bf16 v[24:27], v[166:169], v[206:209], 0
	v_mfma_f32_16x16x32_bf16 v[12:15], v[146:149], v[214:217], 0
	v_mfma_f32_16x16x32_bf16 v[8:11], v[166:169], v[214:217], 0
	v_mfma_f32_16x16x32_bf16 v[60:63], v[162:165], v[194:197], v[60:63]
	v_mfma_f32_16x16x32_bf16 v[56:59], v[170:173], v[194:197], v[56:59]
	v_mfma_f32_16x16x32_bf16 v[44:47], v[162:165], v[202:205], v[44:47]
	v_mfma_f32_16x16x32_bf16 v[40:43], v[170:173], v[202:205], v[40:43]
	v_mfma_f32_16x16x32_bf16 v[28:31], v[162:165], v[210:213], v[28:31]
	v_mfma_f32_16x16x32_bf16 v[24:27], v[170:173], v[210:213], v[24:27]
	v_mfma_f32_16x16x32_bf16 v[12:15], v[162:165], v[218:221], v[12:15]
	v_mfma_f32_16x16x32_bf16 v[8:11], v[170:173], v[218:221], v[8:11]
	s_setprio 0
	s_setprio 1
	v_mfma_f32_16x16x32_bf16 v[52:55], v[174:177], v[190:193], 0
	v_mfma_f32_16x16x32_bf16 v[48:51], v[182:185], v[190:193], 0
	v_mfma_f32_16x16x32_bf16 v[36:39], v[174:177], v[198:201], 0
	v_mfma_f32_16x16x32_bf16 v[32:35], v[182:185], v[198:201], 0
	v_mfma_f32_16x16x32_bf16 v[20:23], v[174:177], v[206:209], 0
	v_mfma_f32_16x16x32_bf16 v[16:19], v[182:185], v[206:209], 0
	v_mfma_f32_16x16x32_bf16 v[4:7], v[174:177], v[214:217], 0
	v_mfma_f32_16x16x32_bf16 v[0:3], v[182:185], v[214:217], 0
	v_mfma_f32_16x16x32_bf16 v[52:55], v[178:181], v[194:197], v[52:55]
	v_mfma_f32_16x16x32_bf16 v[48:51], v[186:189], v[194:197], v[48:51]
	v_mfma_f32_16x16x32_bf16 v[36:39], v[178:181], v[202:205], v[36:39]
	v_mfma_f32_16x16x32_bf16 v[32:35], v[186:189], v[202:205], v[32:35]
	v_mfma_f32_16x16x32_bf16 v[20:23], v[178:181], v[210:213], v[20:23]
	v_mfma_f32_16x16x32_bf16 v[16:19], v[186:189], v[210:213], v[16:19]
	v_mfma_f32_16x16x32_bf16 v[4:7], v[178:181], v[218:221], v[4:7]
	v_mfma_f32_16x16x32_bf16 v[0:3], v[186:189], v[218:221], v[0:3]
	s_setprio 0
	s_barrier
	s_branch .Lkmid_P6

; #define PG8_STAGE(bufoff, gbase, voff) do { _Pragma("unroll") for (int _i = 0; _i < 2; ++_i) \
;         __builtin_amdgcn_global_load_lds((const unsigned*)((const char*)(gbase) + (voff)[_i]), (PG8_LAS unsigned*)(lds + (bufoff) + ldsw + _i * 8192), 16, 0, PG8_LOAD_AUX); } while (0)
; #define PG8_LDA(dst, b, h) do { _Pragma("unroll") for (int m = 0; m < 4; ++m) _Pragma("unroll") for (int k = 0; k < 2; ++k) dst[m][k] = *(const PG8_LAS bf16x8*)(lds + PG8_SA(b, h) + aoff + m * 2048 + k * 1024); } while (0)
; #define PG8_LDB(dst, b, h) do { _Pragma("unroll") for (int n = 0; n < 2; ++n) _Pragma("unroll") for (int k = 0; k < 2; ++k) dst[n][k] = *(const PG8_LAS bf16x8*)(lds + PG8_SB(b, h) + boff + n * 2048 + k * 1024); } while (0)
; #define PG8_SCHED __builtin_amdgcn_sched_barrier(0)
;     __host__ __device__ bool next(int i, Unit& u) const {
;         const long L = (long)i * G + c; if (L >= nwg) return false;
;         int wgid = (int)L; { const int q = nwg / NXCD, r = nwg % NXCD, xcd = wgid % NXCD, off = wgid / NXCD; wgid = (xcd < r ? xcd * (q + 1) : r * (q + 1) + (xcd - r) * q) + off; }
;         const int nig = WGM * nN, gid = wgid / nig, fm = gid * WGM, gsz = (nM - fm) < WGM ? (nM - fm) : WGM;
;         u.pm = fm + ((wgid % nig) % gsz); u.pn = (wgid % nig) / gsz; return true;
; template <class Epi, class Sched, bool ALIGN_EPI = false, bool SP2 = false>
; __device__ __forceinline__ void gemm_phase(PG8_LAS unsigned char* lds, const Gemm g, const Sched& S, const Epi& E) {
;     ...
;         const bool has_next = S.next(ui + 1, nxt);
;         const char* nA = has_next ? (const char*)g.A + (size_t)nxt.pm * tstepA + (size_t)nxt.pn * apn : cA; const char* nB = has_next ? (const char*)g.Bt + (size_t)nxt.pn * tstepB : cB;
;         for (int t = 0; t < nt; t += 2) {
;             const bool last = (t == nt - 2);
;             const char* a1 = cA + (size_t)(t + 1) * kstep;
;             const char* a2 = last ? nA : cA + (size_t)(t + 2) * kstep; const char* b2 = last ? nB : cB + (size_t)(t + 2) * kstep;
;             const char* a3 = a2 + kstep; const char* b3 = b2 + kstep;
;             if (last && has_next) S.a_ready(nxt);
;             if constexpr (SP2) {
;             PG8_LDB(B0, 0, 0); PG8_LDB(B1, 0, 1); PG8_SCHED; PG8_LDA(At, 0, 0); PG8_STAGE(PG8_SA(1, 1), a1 + hstepA, voffA);
.LBB0_669:
	ds_read_b128 v[146:149], v158
	ds_read_b128 v[164:167], v158 offset:1024
	ds_read_b128 v[168:171], v158 offset:2048
	ds_read_b128 v[172:175], v158 offset:3072
	ds_read_b128 v[176:179], v159
	ds_read_b128 v[180:183], v159 offset:1024
	ds_read_b128 v[184:187], v159 offset:2048
	ds_read_b128 v[188:191], v159 offset:3072
	ds_read_b128 v[192:195], v160
	ds_read_b128 v[196:199], v160 offset:1024
	ds_read_b128 v[200:203], v160 offset:2048
	ds_read_b128 v[204:207], v160 offset:3072
	ds_read_b128 v[208:211], v160 offset:4096
	ds_read_b128 v[212:215], v160 offset:5120
	ds_read_b128 v[216:219], v160 offset:6144
	ds_read_b128 v[220:223], v160 offset:7168
	s_add_i32 s49, s49, 1
	s_mul_i32 s2, s49, s50
	s_mul_hi_u32 s3, s49, s53
	s_add_i32 s3, s3, s2
	s_mul_i32 s2, s49, s53
	v_readlane_b32 s15, v239, 0
	s_add_u32 s18, s2, s15
	s_addc_u32 s19, s3, s41
	v_cmp_gt_i64_e32 vcc, s[18:19], v[144:145]
	v_cmp_lt_i64_e64 s[2:3], s[18:19], v[142:143]
	s_cbranch_vccnz .LBB0_671
	s_ashr_i32 s14, s18, 31
	s_lshr_b32 s14, s14, 29
	s_add_i32 s14, s18, s14
	s_ashr_i32 s15, s14, 3
	s_and_b32 s14, s14, -8
	s_sub_i32 s14, s18, s14
	s_cmp_lt_i32 s14, 0
	s_cselect_b32 s16, s42, 0x160
	s_mul_i32 s14, s14, s16
	s_add_i32 s14, s14, s15
	s_mul_hi_i32 s15, s14, 0x2e8ba2e9
	s_lshr_b32 s16, s15, 31
	s_ashr_i32 s15, s15, 4
	s_add_i32 s15, s15, s16
	s_lshl_b32 s16, s15, 2
	s_sub_i32 s17, 0x80, s16
	s_min_i32 s17, s17, 4
	s_abs_i32 s18, s17
	v_cvt_f32_u32_e32 v0, s18
	s_sub_i32 s24, 0, s18
	s_mulk_i32 s15, 0x58
	s_sub_i32 s15, s14, s15
	v_rcp_iflag_f32_e32 v0, v0
	s_abs_i32 s14, s15
	s_xor_b32 s19, s15, s17
	s_ashr_i32 s19, s19, 31
	v_mul_f32_e32 v0, 0x4f7ffffe, v0
	v_cvt_u32_f32_e32 v0, v0
	s_nop 0
	v_readfirstlane_b32 s25, v0
	s_mul_i32 s24, s24, s25
	s_mul_hi_u32 s24, s25, s24
	s_add_i32 s25, s25, s24
	s_mul_hi_u32 s24, s14, s25
	s_mul_i32 s25, s24, s18
	s_sub_i32 s14, s14, s25
	s_add_i32 s26, s24, 1
	s_sub_i32 s25, s14, s18
	s_cmp_ge_u32 s14, s18
	s_cselect_b32 s24, s26, s24
	s_cselect_b32 s14, s25, s14
	s_add_i32 s25, s24, 1
	s_cmp_ge_u32 s14, s18
	s_cselect_b32 s14, s25, s24
	s_xor_b32 s14, s14, s19
	s_sub_i32 s14, s14, s19
	s_mul_i32 s17, s14, s17
	s_sub_i32 s15, s15, s17
	s_add_i32 s16, s16, s15
; #define PG8_STAGE(bufoff, gbase, voff) do { _Pragma("unroll") for (int _i = 0; _i < 2; ++_i) \
;         __builtin_amdgcn_global_load_lds((const unsigned*)((const char*)(gbase) + (voff)[_i]), (PG8_LAS unsigned*)(lds + (bufoff) + ldsw + _i * 8192), 16, 0, PG8_LOAD_AUX); } while (0)
; #define PG8_LDA(dst, b, h) do { _Pragma("unroll") for (int m = 0; m < 4; ++m) _Pragma("unroll") for (int k = 0; k < 2; ++k) dst[m][k] = *(const PG8_LAS bf16x8*)(lds + PG8_SA(b, h) + aoff + m * 2048 + k * 1024); } while (0)
; #define PG8_LDB(dst, b, h) do { _Pragma("unroll") for (int n = 0; n < 2; ++n) _Pragma("unroll") for (int k = 0; k < 2; ++k) dst[n][k] = *(const PG8_LAS bf16x8*)(lds + PG8_SB(b, h) + boff + n * 2048 + k * 1024); } while (0)
; #define PG8_WAIT_V(n) asm volatile("s_waitcnt vmcnt(" #n ")" ::: "memory")
; #define PG8_WAIT_L(n) asm volatile("s_waitcnt lgkmcnt(" #n ")" ::: "memory")
; #define PG8_BAR __builtin_amdgcn_s_barrier()
; #define PG8_SCHED __builtin_amdgcn_sched_barrier(0)
; template <class Epi, class Sched, bool ALIGN_EPI = false, bool SP2 = false>
; __device__ __forceinline__ void gemm_phase(PG8_LAS unsigned char* lds, const Gemm g, const Sched& S, const Epi& E) {
;     ...
;         const char* nA = has_next ? (const char*)g.A + (size_t)nxt.pm * tstepA + (size_t)nxt.pn * apn : cA; const char* nB = has_next ? (const char*)g.Bt + (size_t)nxt.pn * tstepB : cB;
;         for (int t = 0; t < nt; t += 2) {
;             const bool last = (t == nt - 2);
;             const char* a1 = cA + (size_t)(t + 1) * kstep;
;             const char* a2 = last ? nA : cA + (size_t)(t + 2) * kstep; const char* b2 = last ? nB : cB + (size_t)(t + 2) * kstep;
;             const char* a3 = a2 + kstep; const char* b3 = b2 + kstep;
;             if (last && has_next) S.a_ready(nxt);
;             if constexpr (SP2) {
;             PG8_LDB(B0, 0, 0); PG8_LDB(B1, 0, 1); PG8_SCHED; PG8_LDA(At, 0, 0); PG8_STAGE(PG8_SA(1, 1), a1 + hstepA, voffA);
;             PG8_WAIT_V(8); PG8_WAIT_L(0); PG8_BAR; PG8_MMA(0, 0, At, B0); PG8_MMA(0, 1, At, B1); PG8_BAR; PG8_SCHED;
;             PG8_LDA(At, 0, 1); PG8_STAGE(PG8_SB(0, 0), b2, voffB); PG8_STAGE(PG8_SB(0, 1), b2 + hstepB, voffB); PG8_STAGE(PG8_SA(0, 0), a2, voffA);
;             PG8_WAIT_V(8); PG8_WAIT_L(0); PG8_BAR; PG8_MMA(1, 0, At, B0); PG8_MMA(1, 1, At, B1); PG8_BAR; PG8_SCHED;
.LBB0_671:
	s_ashr_i32 s17, s16, 31
	s_lshl_b64 s[18:19], s[16:17], 19
	s_add_u32 s18, s30, s18
	s_addc_u32 s19, s31, s19
	s_and_b64 s[24:25], s[2:3], exec
	s_cselect_b32 s17, s19, s21
	s_cselect_b32 s24, s18, s20
	s_ashr_i32 s15, s14, 31
	s_lshl_b64 s[26:27], s[14:15], 19
	v_readlane_b32 s15, v239, 40
	s_add_u32 s36, s15, s26
	v_readlane_b32 s15, v239, 41
	s_addc_u32 s37, s15, s27
	s_and_b64 s[26:27], s[2:3], exec
	s_cselect_b32 s15, s37, s23
	s_cselect_b32 s25, s36, s22
	s_add_u32 s20, s20, 0x40080
	s_addc_u32 s21, s21, 0
	s_add_u32 s26, s22, 0x100
	s_addc_u32 s27, s23, 0
	s_mov_b32 s28, -2
	s_add_u32 s22, s20, 0xfffc0080
	s_addc_u32 s23, s21, -1
	s_cmp_eq_u32 s28, 12
	s_cselect_b32 s35, s17, s23
	s_cselect_b32 s34, s24, s22
	s_cselect_b32 s23, s15, s27
	s_cselect_b32 s22, s25, s26
	v_lshl_add_u64 v[150:151], s[20:21], 0, v[138:139]
	s_add_i32 m0, s43, 0xc000
	global_load_lds_dwordx4 v[150:151], off
	v_lshl_add_u64 v[150:151], s[20:21], 0, v[140:141]
	s_add_i32 m0, s43, 0xe000
	s_nop 0
	global_load_lds_dwordx4 v[150:151], off
	s_waitcnt vmcnt(8)
	s_waitcnt lgkmcnt(0)
	s_barrier
	s_setprio 1
	s_waitcnt lgkmcnt(0)
	v_mfma_f32_16x16x32_bf16 v[124:127], v[146:149], v[192:195], 0
	v_mfma_f32_16x16x32_bf16 v[120:123], v[168:171], v[192:195], 0
	v_mfma_f32_16x16x32_bf16 v[108:111], v[146:149], v[200:203], 0
	v_mfma_f32_16x16x32_bf16 v[104:107], v[168:171], v[200:203], 0
	v_mfma_f32_16x16x32_bf16 v[92:95], v[146:149], v[208:211], 0
	v_mfma_f32_16x16x32_bf16 v[88:91], v[168:171], v[208:211], 0
	v_mfma_f32_16x16x32_bf16 v[76:79], v[146:149], v[216:219], 0
	v_mfma_f32_16x16x32_bf16 v[72:75], v[168:171], v[216:219], 0
	v_mfma_f32_16x16x32_bf16 v[124:127], v[164:167], v[196:199], v[124:127]
	v_mfma_f32_16x16x32_bf16 v[120:123], v[172:175], v[196:199], v[120:123]
	v_mfma_f32_16x16x32_bf16 v[108:111], v[164:167], v[204:207], v[108:111]
	v_mfma_f32_16x16x32_bf16 v[104:107], v[172:175], v[204:207], v[104:107]
	v_mfma_f32_16x16x32_bf16 v[92:95], v[164:167], v[212:215], v[92:95]
	v_mfma_f32_16x16x32_bf16 v[88:91], v[172:175], v[212:215], v[88:91]
	v_mfma_f32_16x16x32_bf16 v[76:79], v[164:167], v[220:223], v[76:79]
	v_mfma_f32_16x16x32_bf16 v[72:75], v[172:175], v[220:223], v[72:75]
	s_setprio 0
	s_setprio 1
	v_mfma_f32_16x16x32_bf16 v[116:119], v[176:179], v[192:195], 0
	v_mfma_f32_16x16x32_bf16 v[112:115], v[184:187], v[192:195], 0
	v_mfma_f32_16x16x32_bf16 v[100:103], v[176:179], v[200:203], 0
	v_mfma_f32_16x16x32_bf16 v[96:99], v[184:187], v[200:203], 0
	v_mfma_f32_16x16x32_bf16 v[84:87], v[176:179], v[208:211], 0
	v_mfma_f32_16x16x32_bf16 v[80:83], v[184:187], v[208:211], 0
	v_mfma_f32_16x16x32_bf16 v[68:71], v[176:179], v[216:219], 0
	v_mfma_f32_16x16x32_bf16 v[64:67], v[184:187], v[216:219], 0
	v_mfma_f32_16x16x32_bf16 v[116:119], v[180:183], v[196:199], v[116:119]
	v_mfma_f32_16x16x32_bf16 v[112:115], v[188:191], v[196:199], v[112:115]
	v_mfma_f32_16x16x32_bf16 v[100:103], v[180:183], v[204:207], v[100:103]
	v_mfma_f32_16x16x32_bf16 v[96:99], v[188:191], v[204:207], v[96:99]
	v_mfma_f32_16x16x32_bf16 v[84:87], v[180:183], v[212:215], v[84:87]
	v_mfma_f32_16x16x32_bf16 v[80:83], v[188:191], v[212:215], v[80:83]
	v_mfma_f32_16x16x32_bf16 v[68:71], v[180:183], v[220:223], v[68:71]
	v_mfma_f32_16x16x32_bf16 v[64:67], v[188:191], v[220:223], v[64:67]
	s_setprio 0
	s_barrier
	s_add_i32 s29, s54, s40
	v_lshl_add_u64 v[150:151], s[22:23], 0, v[130:131]
	s_mov_b32 m0, s29
	ds_read_b128 v[192:195], v160 offset:16384
	ds_read_b128 v[196:199], v160 offset:17408
	ds_read_b128 v[200:203], v160 offset:18432
	ds_read_b128 v[204:207], v160 offset:19456
	ds_read_b128 v[208:211], v160 offset:20480
	ds_read_b128 v[212:215], v160 offset:21504
	ds_read_b128 v[216:219], v160 offset:22528
	ds_read_b128 v[220:223], v160 offset:23552
	global_load_lds_dwordx4 v[150:151], off
	s_add_i32 m0, s29, 0x2000
	s_add_u32 s30, s22, 0x40000
	v_lshl_add_u64 v[224:225], s[22:23], 0, v[134:135]
	s_addc_u32 s31, s23, 0
	s_add_i32 s29, s55, s40
	global_load_lds_dwordx4 v[224:225], off
	v_lshl_add_u64 v[226:227], s[30:31], 0, v[130:131]
	s_mov_b32 m0, s29
	v_lshl_add_u64 v[228:229], s[34:35], 0, v[132:133]
	global_load_lds_dwordx4 v[226:227], off
	v_lshl_add_u64 v[226:227], s[30:31], 0, v[134:135]
	s_add_i32 m0, s29, 0x2000
	s_nop 0
	global_load_lds_dwordx4 v[226:227], off
	v_lshl_add_u64 v[226:227], s[34:35], 0, v[128:129]
	s_mov_b32 m0, s43
	s_nop 0
	global_load_lds_dwordx4 v[226:227], off
	s_mov_b32 m0, s46
	s_nop 0
	global_load_lds_dwordx4 v[228:229], off
	s_waitcnt vmcnt(8)
	s_waitcnt lgkmcnt(0)
	s_barrier
	s_setprio 1
	s_waitcnt lgkmcnt(0)
	v_mfma_f32_16x16x32_bf16 v[60:63], v[146:149], v[192:195], 0
	v_mfma_f32_16x16x32_bf16 v[56:59], v[168:171], v[192:195], 0
	v_mfma_f32_16x16x32_bf16 v[44:47], v[146:149], v[200:203], 0
	v_mfma_f32_16x16x32_bf16 v[40:43], v[168:171], v[200:203], 0
	v_mfma_f32_16x16x32_bf16 v[28:31], v[146:149], v[208:211], 0
	v_mfma_f32_16x16x32_bf16 v[24:27], v[168:171], v[208:211], 0
	v_mfma_f32_16x16x32_bf16 v[12:15], v[146:149], v[216:219], 0
	v_mfma_f32_16x16x32_bf16 v[8:11], v[168:171], v[216:219], 0
	v_mfma_f32_16x16x32_bf16 v[60:63], v[164:167], v[196:199], v[60:63]
	v_mfma_f32_16x16x32_bf16 v[56:59], v[172:175], v[196:199], v[56:59]
	v_mfma_f32_16x16x32_bf16 v[44:47], v[164:167], v[204:207], v[44:47]
	v_mfma_f32_16x16x32_bf16 v[40:43], v[172:175], v[204:207], v[40:43]
	v_mfma_f32_16x16x32_bf16 v[28:31], v[164:167], v[212:215], v[28:31]
	v_mfma_f32_16x16x32_bf16 v[24:27], v[172:175], v[212:215], v[24:27]
	v_mfma_f32_16x16x32_bf16 v[12:15], v[164:167], v[220:223], v[12:15]
	v_mfma_f32_16x16x32_bf16 v[8:11], v[172:175], v[220:223], v[8:11]
	s_setprio 0
	s_setprio 1
	v_mfma_f32_16x16x32_bf16 v[52:55], v[176:179], v[192:195], 0
	v_mfma_f32_16x16x32_bf16 v[48:51], v[184:187], v[192:195], 0
	v_mfma_f32_16x16x32_bf16 v[36:39], v[176:179], v[200:203], 0
	v_mfma_f32_16x16x32_bf16 v[32:35], v[184:187], v[200:203], 0
	v_mfma_f32_16x16x32_bf16 v[20:23], v[176:179], v[208:211], 0
	v_mfma_f32_16x16x32_bf16 v[16:19], v[184:187], v[208:211], 0
	v_mfma_f32_16x16x32_bf16 v[4:7], v[176:179], v[216:219], 0
	v_mfma_f32_16x16x32_bf16 v[0:3], v[184:187], v[216:219], 0
	v_mfma_f32_16x16x32_bf16 v[52:55], v[180:183], v[196:199], v[52:55]
	v_mfma_f32_16x16x32_bf16 v[48:51], v[188:191], v[196:199], v[48:51]
	v_mfma_f32_16x16x32_bf16 v[36:39], v[180:183], v[204:207], v[36:39]
	v_mfma_f32_16x16x32_bf16 v[32:35], v[188:191], v[204:207], v[32:35]
	v_mfma_f32_16x16x32_bf16 v[20:23], v[180:183], v[212:215], v[20:23]
	v_mfma_f32_16x16x32_bf16 v[16:19], v[188:191], v[212:215], v[16:19]
	v_mfma_f32_16x16x32_bf16 v[4:7], v[180:183], v[220:223], v[4:7]
	v_mfma_f32_16x16x32_bf16 v[0:3], v[188:191], v[220:223], v[0:3]
	s_setprio 0
	s_barrier
	s_branch .Lkmid_P7

; #define PG8_STAGE(bufoff, gbase, voff) do { _Pragma("unroll") for (int _i = 0; _i < 2; ++_i) \
;         __builtin_amdgcn_global_load_lds((const unsigned*)((const char*)(gbase) + (voff)[_i]), (PG8_LAS unsigned*)(lds + (bufoff) + ldsw + _i * 8192), 16, 0, PG8_LOAD_AUX); } while (0)
; #define PG8_LDA(dst, b, h) do { _Pragma("unroll") for (int m = 0; m < 4; ++m) _Pragma("unroll") for (int k = 0; k < 2; ++k) dst[m][k] = *(const PG8_LAS bf16x8*)(lds + PG8_SA(b, h) + aoff + m * 2048 + k * 1024); } while (0)
; #define PG8_LDB(dst, b, h) do { _Pragma("unroll") for (int n = 0; n < 2; ++n) _Pragma("unroll") for (int k = 0; k < 2; ++k) dst[n][k] = *(const PG8_LAS bf16x8*)(lds + PG8_SB(b, h) + boff + n * 2048 + k * 1024); } while (0)
; #define PG8_SCHED __builtin_amdgcn_sched_barrier(0)
;     __host__ __device__ bool next(int i, Unit& u) const {
;         const long L = (long)i * G + c; if (L >= nwg) return false;
;         int wgid = (int)L; { const int q = nwg / NXCD, r = nwg % NXCD, xcd = wgid % NXCD, off = wgid / NXCD; wgid = (xcd < r ? xcd * (q + 1) : r * (q + 1) + (xcd - r) * q) + off; }
;         const int nig = WGM * nN, gid = wgid / nig, fm = gid * WGM, gsz = (nM - fm) < WGM ? (nM - fm) : WGM;
;         u.pm = fm + ((wgid % nig) % gsz); u.pn = (wgid % nig) / gsz; return true;
; template <class Epi, class Sched, bool ALIGN_EPI = false, bool SP2 = false>
; __device__ __forceinline__ void gemm_phase(PG8_LAS unsigned char* lds, const Gemm g, const Sched& S, const Epi& E) {
;     ...
;         const bool has_next = S.next(ui + 1, nxt);
;         const char* nA = has_next ? (const char*)g.A + (size_t)nxt.pm * tstepA + (size_t)nxt.pn * apn : cA; const char* nB = has_next ? (const char*)g.Bt + (size_t)nxt.pn * tstepB : cB;
;         for (int t = 0; t < nt; t += 2) {
;             const bool last = (t == nt - 2);
;             const char* a1 = cA + (size_t)(t + 1) * kstep;
;             const char* a2 = last ? nA : cA + (size_t)(t + 2) * kstep; const char* b2 = last ? nB : cB + (size_t)(t + 2) * kstep;
;             const char* a3 = a2 + kstep; const char* b3 = b2 + kstep;
;             if (last && has_next) S.a_ready(nxt);
;             if constexpr (SP2) {
;             PG8_LDB(B0, 0, 0); PG8_LDB(B1, 0, 1); PG8_SCHED; PG8_LDA(At, 0, 0); PG8_STAGE(PG8_SA(1, 1), a1 + hstepA, voffA);
.LBB0_746:
	ds_read_b128 v[146:149], v157
	ds_read_b128 v[162:165], v157 offset:1024
	ds_read_b128 v[166:169], v157 offset:2048
	ds_read_b128 v[170:173], v157 offset:3072
	ds_read_b128 v[174:177], v158
	ds_read_b128 v[178:181], v158 offset:1024
	ds_read_b128 v[182:185], v158 offset:2048
	ds_read_b128 v[186:189], v158 offset:3072
	ds_read_b128 v[190:193], v159
	ds_read_b128 v[194:197], v159 offset:1024
	ds_read_b128 v[198:201], v159 offset:2048
	ds_read_b128 v[202:205], v159 offset:3072
	ds_read_b128 v[206:209], v159 offset:4096
	ds_read_b128 v[210:213], v159 offset:5120
	ds_read_b128 v[214:217], v159 offset:6144
	ds_read_b128 v[218:221], v159 offset:7168
	s_add_i32 s57, s57, 1
	s_mul_i32 s6, s57, s52
	s_mul_hi_u32 s7, s57, s53
	s_add_i32 s7, s7, s6
	s_mul_i32 s6, s57, s53
	v_readlane_b32 s8, v239, 0
	s_add_u32 s6, s6, s8
	s_addc_u32 s7, s7, s54
	v_cmp_gt_i64_e32 vcc, s[6:7], v[144:145]
	v_cmp_lt_i64_e64 s[8:9], s[6:7], v[142:143]
	s_cbranch_vccnz .LBB0_752
	s_ashr_i32 s7, s6, 31
	s_lshr_b32 s7, s7, 29
	s_add_i32 s22, s6, s7
	s_and_b32 s7, s22, -8
	s_sub_i32 s23, s6, s7
	s_cmp_gt_i32 s23, -1
	s_mov_b64 s[6:7], -1
	s_cbranch_scc0 .LBB0_749
	s_lshl_b32 s25, s23, 6
	s_mov_b64 s[6:7], 0

; #define PG8_STAGE(bufoff, gbase, voff) do { _Pragma("unroll") for (int _i = 0; _i < 2; ++_i) \
;         __builtin_amdgcn_global_load_lds((const unsigned*)((const char*)(gbase) + (voff)[_i]), (PG8_LAS unsigned*)(lds + (bufoff) + ldsw + _i * 8192), 16, 0, PG8_LOAD_AUX); } while (0)
; #define PG8_LDA(dst, b, h) do { _Pragma("unroll") for (int m = 0; m < 4; ++m) _Pragma("unroll") for (int k = 0; k < 2; ++k) dst[m][k] = *(const PG8_LAS bf16x8*)(lds + PG8_SA(b, h) + aoff + m * 2048 + k * 1024); } while (0)
; #define PG8_LDB(dst, b, h) do { _Pragma("unroll") for (int n = 0; n < 2; ++n) _Pragma("unroll") for (int k = 0; k < 2; ++k) dst[n][k] = *(const PG8_LAS bf16x8*)(lds + PG8_SB(b, h) + boff + n * 2048 + k * 1024); } while (0)
; #define PG8_WAIT_V(n) asm volatile("s_waitcnt vmcnt(" #n ")" ::: "memory")
; #define PG8_WAIT_L(n) asm volatile("s_waitcnt lgkmcnt(" #n ")" ::: "memory")
; #define PG8_BAR __builtin_amdgcn_s_barrier()
; #define PG8_SCHED __builtin_amdgcn_sched_barrier(0)
; template <class Epi, class Sched, bool ALIGN_EPI = false, bool SP2 = false>
; __device__ __forceinline__ void gemm_phase(PG8_LAS unsigned char* lds, const Gemm g, const Sched& S, const Epi& E) {
;     ...
;         const char* nA = has_next ? (const char*)g.A + (size_t)nxt.pm * tstepA + (size_t)nxt.pn * apn : cA; const char* nB = has_next ? (const char*)g.Bt + (size_t)nxt.pn * tstepB : cB;
;         for (int t = 0; t < nt; t += 2) {
;             const bool last = (t == nt - 2);
;             const char* a1 = cA + (size_t)(t + 1) * kstep;
;             const char* a2 = last ? nA : cA + (size_t)(t + 2) * kstep; const char* b2 = last ? nB : cB + (size_t)(t + 2) * kstep;
;             const char* a3 = a2 + kstep; const char* b3 = b2 + kstep;
;             if (last && has_next) S.a_ready(nxt);
;             if constexpr (SP2) {
;             PG8_LDB(B0, 0, 0); PG8_LDB(B1, 0, 1); PG8_SCHED; PG8_LDA(At, 0, 0); PG8_STAGE(PG8_SA(1, 1), a1 + hstepA, voffA);
;             PG8_WAIT_V(8); PG8_WAIT_L(0); PG8_BAR; PG8_MMA(0, 0, At, B0); PG8_MMA(0, 1, At, B1); PG8_BAR; PG8_SCHED;
;             PG8_LDA(At, 0, 1); PG8_STAGE(PG8_SB(0, 0), b2, voffB); PG8_STAGE(PG8_SB(0, 1), b2 + hstepB, voffB); PG8_STAGE(PG8_SA(0, 0), a2, voffA);
;             PG8_WAIT_V(8); PG8_WAIT_L(0); PG8_BAR; PG8_MMA(1, 0, At, B0); PG8_MMA(1, 1, At, B1); PG8_BAR; PG8_SCHED;
.LBB0_756:
	s_add_u32 s0, s0, 0xb0080
	s_addc_u32 s1, s1, 0
	s_add_u32 s25, s20, 0x100
	s_addc_u32 s26, s21, 0
	s_mov_b32 s27, -2
	s_waitcnt lgkmcnt(0)
	s_add_u32 s20, s0, 0xfff50080
	s_addc_u32 s21, s1, -1
	s_cmp_eq_u32 s27, 40
	s_cselect_b32 s23, s9, s21
	s_cselect_b32 s22, s8, s20
	s_cselect_b32 s21, s41, s26
	s_cselect_b32 s20, s40, s25
	v_lshl_add_u64 v[222:223], s[0:1], 0, v[138:139]
	s_add_i32 m0, s35, 0xc000
	global_load_lds_dwordx4 v[222:223], off
	v_lshl_add_u64 v[222:223], s[0:1], 0, v[140:141]
	s_add_i32 m0, s35, 0xe000
	s_nop 0
	global_load_lds_dwordx4 v[222:223], off
	s_waitcnt vmcnt(8)
	s_waitcnt lgkmcnt(0)
	s_barrier
	s_setprio 1
	s_waitcnt lgkmcnt(0)
	v_mfma_f32_16x16x32_bf16 v[124:127], v[146:149], v[190:193], 0
	v_mfma_f32_16x16x32_bf16 v[120:123], v[166:169], v[190:193], 0
	v_mfma_f32_16x16x32_bf16 v[108:111], v[146:149], v[198:201], 0
	v_mfma_f32_16x16x32_bf16 v[104:107], v[166:169], v[198:201], 0
	v_mfma_f32_16x16x32_bf16 v[92:95], v[146:149], v[206:209], 0
	v_mfma_f32_16x16x32_bf16 v[88:91], v[166:169], v[206:209], 0
	v_mfma_f32_16x16x32_bf16 v[76:79], v[146:149], v[214:217], 0
	v_mfma_f32_16x16x32_bf16 v[72:75], v[166:169], v[214:217], 0
	v_mfma_f32_16x16x32_bf16 v[124:127], v[162:165], v[194:197], v[124:127]
	v_mfma_f32_16x16x32_bf16 v[120:123], v[170:173], v[194:197], v[120:123]
	v_mfma_f32_16x16x32_bf16 v[108:111], v[162:165], v[202:205], v[108:111]
	v_mfma_f32_16x16x32_bf16 v[104:107], v[170:173], v[202:205], v[104:107]
	v_mfma_f32_16x16x32_bf16 v[92:95], v[162:165], v[210:213], v[92:95]
	v_mfma_f32_16x16x32_bf16 v[88:91], v[170:173], v[210:213], v[88:91]
	v_mfma_f32_16x16x32_bf16 v[76:79], v[162:165], v[218:221], v[76:79]
	v_mfma_f32_16x16x32_bf16 v[72:75], v[170:173], v[218:221], v[72:75]
	s_setprio 0
	s_setprio 1
	v_mfma_f32_16x16x32_bf16 v[116:119], v[174:177], v[190:193], 0
	v_mfma_f32_16x16x32_bf16 v[112:115], v[182:185], v[190:193], 0
	v_mfma_f32_16x16x32_bf16 v[100:103], v[174:177], v[198:201], 0
	v_mfma_f32_16x16x32_bf16 v[96:99], v[182:185], v[198:201], 0
	v_mfma_f32_16x16x32_bf16 v[84:87], v[174:177], v[206:209], 0
	v_mfma_f32_16x16x32_bf16 v[80:83], v[182:185], v[206:209], 0
	v_mfma_f32_16x16x32_bf16 v[68:71], v[174:177], v[214:217], 0
	v_mfma_f32_16x16x32_bf16 v[64:67], v[182:185], v[214:217], 0
	v_mfma_f32_16x16x32_bf16 v[116:119], v[178:181], v[194:197], v[116:119]
	v_mfma_f32_16x16x32_bf16 v[112:115], v[186:189], v[194:197], v[112:115]
	v_mfma_f32_16x16x32_bf16 v[100:103], v[178:181], v[202:205], v[100:103]
	v_mfma_f32_16x16x32_bf16 v[96:99], v[186:189], v[202:205], v[96:99]
	v_mfma_f32_16x16x32_bf16 v[84:87], v[178:181], v[210:213], v[84:87]
	v_mfma_f32_16x16x32_bf16 v[80:83], v[186:189], v[210:213], v[80:83]
	v_mfma_f32_16x16x32_bf16 v[68:71], v[178:181], v[218:221], v[68:71]
	v_mfma_f32_16x16x32_bf16 v[64:67], v[186:189], v[218:221], v[64:67]
	s_setprio 0
	s_barrier
	s_add_i32 s28, s55, s34
	v_lshl_add_u64 v[222:223], s[20:21], 0, v[130:131]
	s_mov_b32 m0, s28
	ds_read_b128 v[190:193], v159 offset:16384
	ds_read_b128 v[194:197], v159 offset:17408
	ds_read_b128 v[198:201], v159 offset:18432
	ds_read_b128 v[202:205], v159 offset:19456
	ds_read_b128 v[206:209], v159 offset:20480
	ds_read_b128 v[210:213], v159 offset:21504
	ds_read_b128 v[214:217], v159 offset:22528
	ds_read_b128 v[218:221], v159 offset:23552
	global_load_lds_dwordx4 v[222:223], off
	s_add_i32 m0, s28, 0x2000
	s_add_u32 s28, s20, 0x2c000
	v_lshl_add_u64 v[224:225], s[20:21], 0, v[134:135]
	s_addc_u32 s29, s21, 0
	s_add_i32 s30, s56, s34
	global_load_lds_dwordx4 v[224:225], off
	v_lshl_add_u64 v[226:227], s[28:29], 0, v[130:131]
	s_mov_b32 m0, s30
	v_lshl_add_u64 v[228:229], s[22:23], 0, v[132:133]
	global_load_lds_dwordx4 v[226:227], off
	v_lshl_add_u64 v[226:227], s[28:29], 0, v[134:135]
	s_add_i32 m0, s30, 0x2000
	s_nop 0
	global_load_lds_dwordx4 v[226:227], off
	v_lshl_add_u64 v[226:227], s[22:23], 0, v[128:129]
	s_mov_b32 m0, s35
	s_nop 0
	global_load_lds_dwordx4 v[226:227], off
	s_mov_b32 m0, s42
	s_nop 0
	global_load_lds_dwordx4 v[228:229], off
	s_waitcnt vmcnt(8)
	s_waitcnt lgkmcnt(0)
	s_barrier
	s_setprio 1
	s_waitcnt lgkmcnt(0)
	v_mfma_f32_16x16x32_bf16 v[60:63], v[146:149], v[190:193], 0
	v_mfma_f32_16x16x32_bf16 v[56:59], v[166:169], v[190:193], 0
	v_mfma_f32_16x16x32_bf16 v[44:47], v[146:149], v[198:201], 0
	v_mfma_f32_16x16x32_bf16 v[40:43], v[166:169], v[198:201], 0
	v_mfma_f32_16x16x32_bf16 v[28:31], v[146:149], v[206:209], 0
	v_mfma_f32_16x16x32_bf16 v[24:27], v[166:169], v[206:209], 0
	v_mfma_f32_16x16x32_bf16 v[12:15], v[146:149], v[214:217], 0
	v_mfma_f32_16x16x32_bf16 v[8:11], v[166:169], v[214:217], 0
	v_mfma_f32_16x16x32_bf16 v[60:63], v[162:165], v[194:197], v[60:63]
	v_mfma_f32_16x16x32_bf16 v[56:59], v[170:173], v[194:197], v[56:59]
	v_mfma_f32_16x16x32_bf16 v[44:47], v[162:165], v[202:205], v[44:47]
	v_mfma_f32_16x16x32_bf16 v[40:43], v[170:173], v[202:205], v[40:43]
	v_mfma_f32_16x16x32_bf16 v[28:31], v[162:165], v[210:213], v[28:31]
	v_mfma_f32_16x16x32_bf16 v[24:27], v[170:173], v[210:213], v[24:27]
	v_mfma_f32_16x16x32_bf16 v[12:15], v[162:165], v[218:221], v[12:15]
	v_mfma_f32_16x16x32_bf16 v[8:11], v[170:173], v[218:221], v[8:11]
	s_setprio 0
	s_setprio 1
	v_mfma_f32_16x16x32_bf16 v[52:55], v[174:177], v[190:193], 0
	v_mfma_f32_16x16x32_bf16 v[48:51], v[182:185], v[190:193], 0
	v_mfma_f32_16x16x32_bf16 v[36:39], v[174:177], v[198:201], 0
	v_mfma_f32_16x16x32_bf16 v[32:35], v[182:185], v[198:201], 0
	v_mfma_f32_16x16x32_bf16 v[20:23], v[174:177], v[206:209], 0
	v_mfma_f32_16x16x32_bf16 v[16:19], v[182:185], v[206:209], 0
	v_mfma_f32_16x16x32_bf16 v[4:7], v[174:177], v[214:217], 0
	v_mfma_f32_16x16x32_bf16 v[0:3], v[182:185], v[214:217], 0
	v_mfma_f32_16x16x32_bf16 v[52:55], v[178:181], v[194:197], v[52:55]
	v_mfma_f32_16x16x32_bf16 v[48:51], v[186:189], v[194:197], v[48:51]
	v_mfma_f32_16x16x32_bf16 v[36:39], v[178:181], v[202:205], v[36:39]
	v_mfma_f32_16x16x32_bf16 v[32:35], v[186:189], v[202:205], v[32:35]
	v_mfma_f32_16x16x32_bf16 v[20:23], v[178:181], v[210:213], v[20:23]
	v_mfma_f32_16x16x32_bf16 v[16:19], v[186:189], v[210:213], v[16:19]
	v_mfma_f32_16x16x32_bf16 v[4:7], v[178:181], v[218:221], v[4:7]
	v_mfma_f32_16x16x32_bf16 v[0:3], v[186:189], v[218:221], v[0:3]
	s_setprio 0
	s_barrier
	s_branch .Lkmid_P8

; #define PG8_STAGE(bufoff, gbase, voff) do { _Pragma("unroll") for (int _i = 0; _i < 2; ++_i) \
;         __builtin_amdgcn_global_load_lds((const unsigned*)((const char*)(gbase) + (voff)[_i]), (PG8_LAS unsigned*)(lds + (bufoff) + ldsw + _i * 8192), 16, 0, PG8_LOAD_AUX); } while (0)
; #define PG8_LDA(dst, b, h) do { _Pragma("unroll") for (int m = 0; m < 4; ++m) _Pragma("unroll") for (int k = 0; k < 2; ++k) dst[m][k] = *(const PG8_LAS bf16x8*)(lds + PG8_SA(b, h) + aoff + m * 2048 + k * 1024); } while (0)
; #define PG8_LDB(dst, b, h) do { _Pragma("unroll") for (int n = 0; n < 2; ++n) _Pragma("unroll") for (int k = 0; k < 2; ++k) dst[n][k] = *(const PG8_LAS bf16x8*)(lds + PG8_SB(b, h) + boff + n * 2048 + k * 1024); } while (0)
; #define PG8_SCHED __builtin_amdgcn_sched_barrier(0)
;     __host__ __device__ bool next(int i, Unit& u) const {
;         const long L = (long)i * G + c; if (L >= nwg) return false;
;         int wgid = (int)L; { const int q = nwg / NXCD, r = nwg % NXCD, xcd = wgid % NXCD, off = wgid / NXCD; wgid = (xcd < r ? xcd * (q + 1) : r * (q + 1) + (xcd - r) * q) + off; }
;         const int nig = WGM * nN, gid = wgid / nig, fm = gid * WGM, gsz = (nM - fm) < WGM ? (nM - fm) : WGM;
;         u.pm = fm + ((wgid % nig) % gsz); u.pn = (wgid % nig) / gsz; return true;
; template <class Epi, class Sched, bool ALIGN_EPI = false, bool SP2 = false>
; __device__ __forceinline__ void gemm_phase(PG8_LAS unsigned char* lds, const Gemm g, const Sched& S, const Epi& E) {
;     ...
;         const bool has_next = S.next(ui + 1, nxt);
;         const char* nA = has_next ? (const char*)g.A + (size_t)nxt.pm * tstepA + (size_t)nxt.pn * apn : cA; const char* nB = has_next ? (const char*)g.Bt + (size_t)nxt.pn * tstepB : cB;
;         for (int t = 0; t < nt; t += 2) {
;             const bool last = (t == nt - 2);
;             const char* a1 = cA + (size_t)(t + 1) * kstep;
;             const char* a2 = last ? nA : cA + (size_t)(t + 2) * kstep; const char* b2 = last ? nB : cB + (size_t)(t + 2) * kstep;
;             const char* a3 = a2 + kstep; const char* b3 = b2 + kstep;
;             if (last && has_next) S.a_ready(nxt);
;             if constexpr (SP2) {
;             PG8_LDB(B0, 0, 0); PG8_LDB(B1, 0, 1); PG8_SCHED; PG8_LDA(At, 0, 0); PG8_STAGE(PG8_SA(1, 1), a1 + hstepA, voffA);
.LBB0_843:
	ds_read_b128 v[164:167], v159
	ds_read_b128 v[168:171], v159 offset:1024
	ds_read_b128 v[172:175], v159 offset:2048
	ds_read_b128 v[176:179], v159 offset:3072
	ds_read_b128 v[180:183], v160
	ds_read_b128 v[184:187], v160 offset:1024
	ds_read_b128 v[188:191], v160 offset:2048
	ds_read_b128 v[192:195], v160 offset:3072
	ds_read_b128 v[196:199], v161
	ds_read_b128 v[200:203], v161 offset:1024
	ds_read_b128 v[204:207], v161 offset:2048
	ds_read_b128 v[208:211], v161 offset:3072
	ds_read_b128 v[212:215], v161 offset:4096
	ds_read_b128 v[216:219], v161 offset:5120
	ds_read_b128 v[220:223], v161 offset:6144
	ds_read_b128 v[224:227], v161 offset:7168
	s_add_i32 s52, s52, 1
	s_mul_i32 s4, s52, s53
	s_mul_hi_u32 s5, s52, s33
	s_add_i32 s5, s5, s4
	s_mul_i32 s4, s52, s33
	v_readlane_b32 s7, v239, 0
	s_add_u32 s22, s4, s7
	s_addc_u32 s23, s5, s54
	v_cmp_gt_i64_e32 vcc, s[22:23], v[146:147]
	v_cmp_lt_i64_e64 s[4:5], s[22:23], v[144:145]
	s_cbranch_vccnz .LBB0_849
	s_ashr_i32 s7, s22, 31
	s_lshr_b32 s7, s7, 29
	s_add_i32 s7, s22, s7
	s_and_b32 s23, s7, -8
	s_sub_i32 s24, s22, s23
	s_cmp_gt_i32 s24, -1
	s_mov_b64 s[22:23], -1
	s_cbranch_scc0 .LBB0_846
	s_lshl_b32 s25, s24, 6
	s_mov_b64 s[22:23], 0

; #define PG8_STAGE(bufoff, gbase, voff) do { _Pragma("unroll") for (int _i = 0; _i < 2; ++_i) \
;         __builtin_amdgcn_global_load_lds((const unsigned*)((const char*)(gbase) + (voff)[_i]), (PG8_LAS unsigned*)(lds + (bufoff) + ldsw + _i * 8192), 16, 0, PG8_LOAD_AUX); } while (0)
; #define PG8_LDA(dst, b, h) do { _Pragma("unroll") for (int m = 0; m < 4; ++m) _Pragma("unroll") for (int k = 0; k < 2; ++k) dst[m][k] = *(const PG8_LAS bf16x8*)(lds + PG8_SA(b, h) + aoff + m * 2048 + k * 1024); } while (0)
; #define PG8_LDB(dst, b, h) do { _Pragma("unroll") for (int n = 0; n < 2; ++n) _Pragma("unroll") for (int k = 0; k < 2; ++k) dst[n][k] = *(const PG8_LAS bf16x8*)(lds + PG8_SB(b, h) + boff + n * 2048 + k * 1024); } while (0)
; #define PG8_WAIT_V(n) asm volatile("s_waitcnt vmcnt(" #n ")" ::: "memory")
; #define PG8_WAIT_L(n) asm volatile("s_waitcnt lgkmcnt(" #n ")" ::: "memory")
; #define PG8_BAR __builtin_amdgcn_s_barrier()
; #define PG8_SCHED __builtin_amdgcn_sched_barrier(0)
; template <class Epi, class Sched, bool ALIGN_EPI = false, bool SP2 = false>
; __device__ __forceinline__ void gemm_phase(PG8_LAS unsigned char* lds, const Gemm g, const Sched& S, const Epi& E) {
;     ...
;         const char* nA = has_next ? (const char*)g.A + (size_t)nxt.pm * tstepA + (size_t)nxt.pn * apn : cA; const char* nB = has_next ? (const char*)g.Bt + (size_t)nxt.pn * tstepB : cB;
;         for (int t = 0; t < nt; t += 2) {
;             const bool last = (t == nt - 2);
;             const char* a1 = cA + (size_t)(t + 1) * kstep;
;             const char* a2 = last ? nA : cA + (size_t)(t + 2) * kstep; const char* b2 = last ? nB : cB + (size_t)(t + 2) * kstep;
;             const char* a3 = a2 + kstep; const char* b3 = b2 + kstep;
;             if (last && has_next) S.a_ready(nxt);
;             if constexpr (SP2) {
;             PG8_LDB(B0, 0, 0); PG8_LDB(B1, 0, 1); PG8_SCHED; PG8_LDA(At, 0, 0); PG8_STAGE(PG8_SA(1, 1), a1 + hstepA, voffA);
;             PG8_WAIT_V(8); PG8_WAIT_L(0); PG8_BAR; PG8_MMA(0, 0, At, B0); PG8_MMA(0, 1, At, B1); PG8_BAR; PG8_SCHED;
;             PG8_LDA(At, 0, 1); PG8_STAGE(PG8_SB(0, 0), b2, voffB); PG8_STAGE(PG8_SB(0, 1), b2 + hstepB, voffB); PG8_STAGE(PG8_SA(0, 0), a2, voffA);
;             PG8_WAIT_V(8); PG8_WAIT_L(0); PG8_BAR; PG8_MMA(1, 0, At, B0); PG8_MMA(1, 1, At, B1); PG8_BAR; PG8_SCHED;
.LBB0_849:
	s_ashr_i32 s41, s40, 31
	s_lshl_b64 s[22:23], s[40:41], 19
	s_add_u32 s42, s30, s22
	s_addc_u32 s43, s31, s23
	s_and_b64 s[22:23], s[4:5], exec
	s_cselect_b32 s7, s43, s1
	s_cselect_b32 s24, s42, s0
	s_ashr_i32 s37, s36, 31
	s_lshl_b64 s[22:23], s[36:37], 19
	v_readlane_b32 s26, v239, 36
	v_readlane_b32 s27, v239, 37
	s_add_u32 s46, s26, s22
	s_addc_u32 s47, s27, s23
	s_and_b64 s[22:23], s[4:5], exec
	s_cselect_b32 s25, s47, s21
	s_cselect_b32 s26, s46, s20
	s_add_u32 s0, s0, 0x40080
	s_addc_u32 s1, s1, 0
	s_add_u32 s27, s20, 0x100
	s_addc_u32 s28, s21, 0
	s_mov_b32 s29, -2
	s_waitcnt lgkmcnt(0)
	s_add_u32 s20, s0, 0xfffc0080
	s_addc_u32 s21, s1, -1
	s_cmp_eq_u32 s29, 12
	s_cselect_b32 s23, s7, s21
	s_cselect_b32 s22, s24, s20
	s_cselect_b32 s21, s25, s28
	s_cselect_b32 s20, s26, s27
	v_lshl_add_u64 v[148:149], s[0:1], 0, v[140:141]
	s_add_i32 m0, s35, 0xc000
	global_load_lds_dwordx4 v[148:149], off
	v_lshl_add_u64 v[148:149], s[0:1], 0, v[142:143]
	s_add_i32 m0, s35, 0xe000
	s_nop 0
	global_load_lds_dwordx4 v[148:149], off
	s_waitcnt vmcnt(8)
	s_waitcnt lgkmcnt(0)
	s_barrier
	s_setprio 1
	s_waitcnt lgkmcnt(0)
	v_mfma_f32_16x16x32_bf16 v[124:127], v[164:167], v[196:199], 0
	v_mfma_f32_16x16x32_bf16 v[120:123], v[172:175], v[196:199], 0
	v_mfma_f32_16x16x32_bf16 v[108:111], v[164:167], v[204:207], 0
	v_mfma_f32_16x16x32_bf16 v[104:107], v[172:175], v[204:207], 0
	v_mfma_f32_16x16x32_bf16 v[92:95], v[164:167], v[212:215], 0
	v_mfma_f32_16x16x32_bf16 v[88:91], v[172:175], v[212:215], 0
	v_mfma_f32_16x16x32_bf16 v[76:79], v[164:167], v[220:223], 0
	v_mfma_f32_16x16x32_bf16 v[72:75], v[172:175], v[220:223], 0
	v_mfma_f32_16x16x32_bf16 v[124:127], v[168:171], v[200:203], v[124:127]
	v_mfma_f32_16x16x32_bf16 v[120:123], v[176:179], v[200:203], v[120:123]
	v_mfma_f32_16x16x32_bf16 v[108:111], v[168:171], v[208:211], v[108:111]
	v_mfma_f32_16x16x32_bf16 v[104:107], v[176:179], v[208:211], v[104:107]
	v_mfma_f32_16x16x32_bf16 v[92:95], v[168:171], v[216:219], v[92:95]
	v_mfma_f32_16x16x32_bf16 v[88:91], v[176:179], v[216:219], v[88:91]
	v_mfma_f32_16x16x32_bf16 v[76:79], v[168:171], v[224:227], v[76:79]
	v_mfma_f32_16x16x32_bf16 v[72:75], v[176:179], v[224:227], v[72:75]
	s_setprio 0
	s_setprio 1
	v_mfma_f32_16x16x32_bf16 v[116:119], v[180:183], v[196:199], 0
	v_mfma_f32_16x16x32_bf16 v[112:115], v[188:191], v[196:199], 0
	v_mfma_f32_16x16x32_bf16 v[100:103], v[180:183], v[204:207], 0
	v_mfma_f32_16x16x32_bf16 v[96:99], v[188:191], v[204:207], 0
	v_mfma_f32_16x16x32_bf16 v[84:87], v[180:183], v[212:215], 0
	v_mfma_f32_16x16x32_bf16 v[80:83], v[188:191], v[212:215], 0
	v_mfma_f32_16x16x32_bf16 v[68:71], v[180:183], v[220:223], 0
	v_mfma_f32_16x16x32_bf16 v[64:67], v[188:191], v[220:223], 0
	v_mfma_f32_16x16x32_bf16 v[116:119], v[184:187], v[200:203], v[116:119]
	v_mfma_f32_16x16x32_bf16 v[112:115], v[192:195], v[200:203], v[112:115]
	v_mfma_f32_16x16x32_bf16 v[100:103], v[184:187], v[208:211], v[100:103]
	v_mfma_f32_16x16x32_bf16 v[96:99], v[192:195], v[208:211], v[96:99]
	v_mfma_f32_16x16x32_bf16 v[84:87], v[184:187], v[216:219], v[84:87]
	v_mfma_f32_16x16x32_bf16 v[80:83], v[192:195], v[216:219], v[80:83]
	v_mfma_f32_16x16x32_bf16 v[68:71], v[184:187], v[224:227], v[68:71]
	v_mfma_f32_16x16x32_bf16 v[64:67], v[192:195], v[224:227], v[64:67]
	s_setprio 0
	s_barrier
	s_add_i32 s30, s61, s34
	v_lshl_add_u64 v[148:149], s[20:21], 0, v[130:131]
	s_mov_b32 m0, s30
	ds_read_b128 v[196:199], v161 offset:16384
	ds_read_b128 v[200:203], v161 offset:17408
	ds_read_b128 v[204:207], v161 offset:18432
	ds_read_b128 v[208:211], v161 offset:19456
	ds_read_b128 v[212:215], v161 offset:20480
	ds_read_b128 v[216:219], v161 offset:21504
	ds_read_b128 v[220:223], v161 offset:22528
	ds_read_b128 v[224:227], v161 offset:23552
	global_load_lds_dwordx4 v[148:149], off
	s_add_i32 m0, s30, 0x2000
	s_add_u32 s30, s20, 0x10000
	v_lshl_add_u64 v[228:229], s[20:21], 0, v[134:135]
	s_addc_u32 s31, s21, 0
	s_add_i32 s37, s62, s34
	global_load_lds_dwordx4 v[228:229], off
	v_lshl_add_u64 v[230:231], s[30:31], 0, v[130:131]
	s_mov_b32 m0, s37
	v_lshl_add_u64 v[232:233], s[22:23], 0, v[132:133]
	global_load_lds_dwordx4 v[230:231], off
	v_lshl_add_u64 v[230:231], s[30:31], 0, v[134:135]
	s_add_i32 m0, s37, 0x2000
	s_nop 0
	global_load_lds_dwordx4 v[230:231], off
	v_lshl_add_u64 v[230:231], s[22:23], 0, v[128:129]
	s_mov_b32 m0, s35
	s_nop 0
	global_load_lds_dwordx4 v[230:231], off
	s_mov_b32 m0, s49
	s_nop 0
	global_load_lds_dwordx4 v[232:233], off
	s_waitcnt vmcnt(8)
	s_waitcnt lgkmcnt(0)
	s_barrier
	s_setprio 1
	s_waitcnt lgkmcnt(0)
	v_mfma_f32_16x16x32_bf16 v[60:63], v[164:167], v[196:199], 0
	v_mfma_f32_16x16x32_bf16 v[56:59], v[172:175], v[196:199], 0
	v_mfma_f32_16x16x32_bf16 v[44:47], v[164:167], v[204:207], 0
	v_mfma_f32_16x16x32_bf16 v[40:43], v[172:175], v[204:207], 0
	v_mfma_f32_16x16x32_bf16 v[28:31], v[164:167], v[212:215], 0
	v_mfma_f32_16x16x32_bf16 v[24:27], v[172:175], v[212:215], 0
	v_mfma_f32_16x16x32_bf16 v[12:15], v[164:167], v[220:223], 0
	v_mfma_f32_16x16x32_bf16 v[8:11], v[172:175], v[220:223], 0
	v_mfma_f32_16x16x32_bf16 v[60:63], v[168:171], v[200:203], v[60:63]
	v_mfma_f32_16x16x32_bf16 v[56:59], v[176:179], v[200:203], v[56:59]
	v_mfma_f32_16x16x32_bf16 v[44:47], v[168:171], v[208:211], v[44:47]
	v_mfma_f32_16x16x32_bf16 v[40:43], v[176:179], v[208:211], v[40:43]
	v_mfma_f32_16x16x32_bf16 v[28:31], v[168:171], v[216:219], v[28:31]
	v_mfma_f32_16x16x32_bf16 v[24:27], v[176:179], v[216:219], v[24:27]
	v_mfma_f32_16x16x32_bf16 v[12:15], v[168:171], v[224:227], v[12:15]
	v_mfma_f32_16x16x32_bf16 v[8:11], v[176:179], v[224:227], v[8:11]
	s_setprio 0
	s_setprio 1
	v_mfma_f32_16x16x32_bf16 v[52:55], v[180:183], v[196:199], 0
	v_mfma_f32_16x16x32_bf16 v[48:51], v[188:191], v[196:199], 0
	v_mfma_f32_16x16x32_bf16 v[36:39], v[180:183], v[204:207], 0
	v_mfma_f32_16x16x32_bf16 v[32:35], v[188:191], v[204:207], 0
	v_mfma_f32_16x16x32_bf16 v[20:23], v[180:183], v[212:215], 0
	v_mfma_f32_16x16x32_bf16 v[16:19], v[188:191], v[212:215], 0
	v_mfma_f32_16x16x32_bf16 v[4:7], v[180:183], v[220:223], 0
	v_mfma_f32_16x16x32_bf16 v[0:3], v[188:191], v[220:223], 0
	v_mfma_f32_16x16x32_bf16 v[52:55], v[184:187], v[200:203], v[52:55]
	v_mfma_f32_16x16x32_bf16 v[48:51], v[192:195], v[200:203], v[48:51]
	v_mfma_f32_16x16x32_bf16 v[36:39], v[184:187], v[208:211], v[36:39]
	v_mfma_f32_16x16x32_bf16 v[32:35], v[192:195], v[208:211], v[32:35]
	v_mfma_f32_16x16x32_bf16 v[20:23], v[184:187], v[216:219], v[20:23]
	v_mfma_f32_16x16x32_bf16 v[16:19], v[192:195], v[216:219], v[16:19]
	v_mfma_f32_16x16x32_bf16 v[4:7], v[184:187], v[224:227], v[4:7]
	v_mfma_f32_16x16x32_bf16 v[0:3], v[192:195], v[224:227], v[0:3]
	s_setprio 0
	s_barrier
	s_branch .Lkmid_P9

; #define PG8_STAGE(bufoff, gbase, voff) do { _Pragma("unroll") for (int _i = 0; _i < 2; ++_i) \
;         __builtin_amdgcn_global_load_lds((const unsigned*)((const char*)(gbase) + (voff)[_i]), (PG8_LAS unsigned*)(lds + (bufoff) + ldsw + _i * 8192), 16, 0, PG8_LOAD_AUX); } while (0)
; #define PG8_LDA(dst, b, h) do { _Pragma("unroll") for (int m = 0; m < 4; ++m) _Pragma("unroll") for (int k = 0; k < 2; ++k) dst[m][k] = *(const PG8_LAS bf16x8*)(lds + PG8_SA(b, h) + aoff + m * 2048 + k * 1024); } while (0)
; #define PG8_LDB(dst, b, h) do { _Pragma("unroll") for (int n = 0; n < 2; ++n) _Pragma("unroll") for (int k = 0; k < 2; ++k) dst[n][k] = *(const PG8_LAS bf16x8*)(lds + PG8_SB(b, h) + boff + n * 2048 + k * 1024); } while (0)
; #define PG8_SCHED __builtin_amdgcn_sched_barrier(0)
;     __host__ __device__ bool next(int i, Unit& u) const {
;         const long L = (long)i * G + c; if (L >= nwg) return false;
;         int wgid = (int)L; { const int q = nwg / NXCD, r = nwg % NXCD, xcd = wgid % NXCD, off = wgid / NXCD; wgid = (xcd < r ? xcd * (q + 1) : r * (q + 1) + (xcd - r) * q) + off; }
;         const int nig = WGM * nN, gid = wgid / nig, fm = gid * WGM, gsz = (nM - fm) < WGM ? (nM - fm) : WGM;
;         u.pm = fm + ((wgid % nig) % gsz); u.pn = (wgid % nig) / gsz; return true;
; template <class Epi, class Sched, bool ALIGN_EPI = false, bool SP2 = false>
; __device__ __forceinline__ void gemm_phase(PG8_LAS unsigned char* lds, const Gemm g, const Sched& S, const Epi& E) {
;     ...
;         const bool has_next = S.next(ui + 1, nxt);
;         const char* nA = has_next ? (const char*)g.A + (size_t)nxt.pm * tstepA + (size_t)nxt.pn * apn : cA; const char* nB = has_next ? (const char*)g.Bt + (size_t)nxt.pn * tstepB : cB;
;         for (int t = 0; t < nt; t += 2) {
;             const bool last = (t == nt - 2);
;             const char* a1 = cA + (size_t)(t + 1) * kstep;
;             const char* a2 = last ? nA : cA + (size_t)(t + 2) * kstep; const char* b2 = last ? nB : cB + (size_t)(t + 2) * kstep;
;             const char* a3 = a2 + kstep; const char* b3 = b2 + kstep;
;             if (last && has_next) S.a_ready(nxt);
;             if constexpr (SP2) {
;             PG8_LDB(B0, 0, 0); PG8_LDB(B1, 0, 1); PG8_SCHED; PG8_LDA(At, 0, 0); PG8_STAGE(PG8_SA(1, 1), a1 + hstepA, voffA);
.LBB0_1013:
	ds_read_b128 v[142:145], v150
	ds_read_b128 v[156:159], v150 offset:1024
	ds_read_b128 v[160:163], v150 offset:2048
	ds_read_b128 v[164:167], v150 offset:3072
	ds_read_b128 v[168:171], v151
	ds_read_b128 v[172:175], v151 offset:1024
	ds_read_b128 v[176:179], v151 offset:2048
	ds_read_b128 v[180:183], v151 offset:3072
	ds_read_b128 v[184:187], v152
	ds_read_b128 v[188:191], v152 offset:1024
	ds_read_b128 v[192:195], v152 offset:2048
	ds_read_b128 v[196:199], v152 offset:3072
	ds_read_b128 v[200:203], v152 offset:4096
	ds_read_b128 v[204:207], v152 offset:5120
	ds_read_b128 v[208:211], v152 offset:6144
	ds_read_b128 v[212:215], v152 offset:7168
	s_add_i32 s72, s72, 1
	s_mul_i32 s6, s72, s67
	s_mul_hi_u32 s7, s72, s68
	s_add_i32 s7, s7, s6
	s_mul_i32 s6, s72, s68
	v_readlane_b32 s8, v239, 0
	s_add_u32 s22, s6, s8
	s_addc_u32 s23, s7, s69
	v_cmp_gt_i64_e64 s[8:9], s[22:23], v[140:141]
	v_cmp_lt_i64_e64 s[6:7], s[22:23], v[138:139]
	s_and_b64 vcc, exec, s[8:9]
	s_cbranch_vccz .LBB0_1040
	s_andn2_b64 vcc, exec, s[8:9]
	s_mov_b64 s[8:9], -1
	s_cbranch_vccz .LBB0_1045

; #define PG8_STAGE(bufoff, gbase, voff) do { _Pragma("unroll") for (int _i = 0; _i < 2; ++_i) \
;         __builtin_amdgcn_global_load_lds((const unsigned*)((const char*)(gbase) + (voff)[_i]), (PG8_LAS unsigned*)(lds + (bufoff) + ldsw + _i * 8192), 16, 0, PG8_LOAD_AUX); } while (0)
; #define PG8_LDA(dst, b, h) do { _Pragma("unroll") for (int m = 0; m < 4; ++m) _Pragma("unroll") for (int k = 0; k < 2; ++k) dst[m][k] = *(const PG8_LAS bf16x8*)(lds + PG8_SA(b, h) + aoff + m * 2048 + k * 1024); } while (0)
; #define PG8_LDB(dst, b, h) do { _Pragma("unroll") for (int n = 0; n < 2; ++n) _Pragma("unroll") for (int k = 0; k < 2; ++k) dst[n][k] = *(const PG8_LAS bf16x8*)(lds + PG8_SB(b, h) + boff + n * 2048 + k * 1024); } while (0)
; #define PG8_WAIT_V(n) asm volatile("s_waitcnt vmcnt(" #n ")" ::: "memory")
; #define PG8_WAIT_L(n) asm volatile("s_waitcnt lgkmcnt(" #n ")" ::: "memory")
; #define PG8_BAR __builtin_amdgcn_s_barrier()
; #define PG8_SCHED __builtin_amdgcn_sched_barrier(0)
; template <class Epi, class Sched, bool ALIGN_EPI = false, bool SP2 = false>
; __device__ __forceinline__ void gemm_phase(PG8_LAS unsigned char* lds, const Gemm g, const Sched& S, const Epi& E) {
;     ...
;         const char* nA = has_next ? (const char*)g.A + (size_t)nxt.pm * tstepA + (size_t)nxt.pn * apn : cA; const char* nB = has_next ? (const char*)g.Bt + (size_t)nxt.pn * tstepB : cB;
;         for (int t = 0; t < nt; t += 2) {
;             const bool last = (t == nt - 2);
;             const char* a1 = cA + (size_t)(t + 1) * kstep;
;             const char* a2 = last ? nA : cA + (size_t)(t + 2) * kstep; const char* b2 = last ? nB : cB + (size_t)(t + 2) * kstep;
;             const char* a3 = a2 + kstep; const char* b3 = b2 + kstep;
;             if (last && has_next) S.a_ready(nxt);
;             if constexpr (SP2) {
;             PG8_LDB(B0, 0, 0); PG8_LDB(B1, 0, 1); PG8_SCHED; PG8_LDA(At, 0, 0); PG8_STAGE(PG8_SA(1, 1), a1 + hstepA, voffA);
;             PG8_WAIT_V(8); PG8_WAIT_L(0); PG8_BAR; PG8_MMA(0, 0, At, B0); PG8_MMA(0, 1, At, B1); PG8_BAR; PG8_SCHED;
;             PG8_LDA(At, 0, 1); PG8_STAGE(PG8_SB(0, 0), b2, voffB); PG8_STAGE(PG8_SB(0, 1), b2 + hstepB, voffB); PG8_STAGE(PG8_SA(0, 0), a2, voffA);
;             PG8_WAIT_V(8); PG8_WAIT_L(0); PG8_BAR; PG8_MMA(1, 0, At, B0); PG8_MMA(1, 1, At, B1); PG8_BAR; PG8_SCHED;
.LBB0_1017:
	s_lshl_b64 s[22:23], s[40:41], 17
	v_readlane_b32 s24, v239, 38
	s_add_u32 s44, s24, s22
	v_readlane_b32 s22, v239, 39
	s_addc_u32 s45, s22, s23
	s_and_b64 s[22:23], s[6:7], exec
	s_cselect_b32 s24, s45, s1
	s_cselect_b32 s25, s44, s0
	s_mov_b32 s26, 0
	s_mov_b64 s[22:23], -1
	s_mov_b64 s[34:35], 0
	s_waitcnt lgkmcnt(0)
	s_add_u32 s30, s20, s26
	s_addc_u32 s31, s21, 0
	s_add_u32 s27, s30, 0x100
	s_addc_u32 s33, s31, 0
	s_and_b64 s[28:29], s[34:35], exec
	s_cselect_b32 s51, s9, s33
	s_cselect_b32 s50, s8, s27
	s_add_u32 s26, s0, s26
	s_addc_u32 s27, s1, 0
	s_add_u32 s28, s26, 0x100
	s_addc_u32 s29, s27, 0
	s_and_b64 s[26:27], s[34:35], exec
	s_cselect_b32 s53, s24, s29
	s_cselect_b32 s52, s25, s28
	s_add_u32 s56, s30, 0x40080
	s_addc_u32 s57, s31, 0
	s_add_i32 s38, s70, s58
	s_add_i32 m0, s47, 0xc000
	s_add_i32 s43, s47, 0xe000
	s_add_i32 s30, s38, 0x2000
	s_add_u32 s54, s52, 0x4000
	s_addc_u32 s55, s53, 0
	s_add_i32 s33, s71, s58
	s_add_i32 s31, s33, 0x2000
	s_add_i32 s29, 0, 0x18000
	s_add_i32 s28, 0, 0x1c000
	s_add_u32 s48, s50, 0x40000
	s_addc_u32 s49, s51, 0
	s_add_i32 s27, s29, s58
	s_add_i32 s26, s27, 0x2000
	s_add_u32 s34, s52, 0x4080
	s_addc_u32 s35, s53, 0
	s_add_i32 s41, s28, s58
	s_add_i32 s39, s41, 0x2000
	v_lshl_add_u64 v[216:217], s[56:57], 0, v[128:129]
	global_load_lds_dwordx4 v[216:217], off
	v_lshl_add_u64 v[216:217], s[56:57], 0, v[132:133]
	s_mov_b32 m0, s43
	s_nop 0
	global_load_lds_dwordx4 v[216:217], off
	s_waitcnt vmcnt(8)
	s_waitcnt lgkmcnt(0)
	s_barrier
	s_setprio 1
	s_waitcnt lgkmcnt(0)
	v_mfma_f32_16x16x32_bf16 v[124:127], v[142:145], v[184:187], 0
	v_mfma_f32_16x16x32_bf16 v[120:123], v[160:163], v[184:187], 0
	v_mfma_f32_16x16x32_bf16 v[108:111], v[142:145], v[192:195], 0
	v_mfma_f32_16x16x32_bf16 v[104:107], v[160:163], v[192:195], 0
	v_mfma_f32_16x16x32_bf16 v[92:95], v[142:145], v[200:203], 0
	v_mfma_f32_16x16x32_bf16 v[88:91], v[160:163], v[200:203], 0
	v_mfma_f32_16x16x32_bf16 v[76:79], v[142:145], v[208:211], 0
	v_mfma_f32_16x16x32_bf16 v[72:75], v[160:163], v[208:211], 0
	v_mfma_f32_16x16x32_bf16 v[124:127], v[156:159], v[188:191], v[124:127]
	v_mfma_f32_16x16x32_bf16 v[120:123], v[164:167], v[188:191], v[120:123]
	v_mfma_f32_16x16x32_bf16 v[108:111], v[156:159], v[196:199], v[108:111]
	v_mfma_f32_16x16x32_bf16 v[104:107], v[164:167], v[196:199], v[104:107]
	v_mfma_f32_16x16x32_bf16 v[92:95], v[156:159], v[204:207], v[92:95]
	v_mfma_f32_16x16x32_bf16 v[88:91], v[164:167], v[204:207], v[88:91]
	v_mfma_f32_16x16x32_bf16 v[76:79], v[156:159], v[212:215], v[76:79]
	v_mfma_f32_16x16x32_bf16 v[72:75], v[164:167], v[212:215], v[72:75]
	s_setprio 0
	s_setprio 1
	v_mfma_f32_16x16x32_bf16 v[116:119], v[168:171], v[184:187], 0
	v_mfma_f32_16x16x32_bf16 v[112:115], v[176:179], v[184:187], 0
	v_mfma_f32_16x16x32_bf16 v[100:103], v[168:171], v[192:195], 0
	v_mfma_f32_16x16x32_bf16 v[96:99], v[176:179], v[192:195], 0
	v_mfma_f32_16x16x32_bf16 v[84:87], v[168:171], v[200:203], 0
	v_mfma_f32_16x16x32_bf16 v[80:83], v[176:179], v[200:203], 0
	v_mfma_f32_16x16x32_bf16 v[68:71], v[168:171], v[208:211], 0
	v_mfma_f32_16x16x32_bf16 v[64:67], v[176:179], v[208:211], 0
	v_mfma_f32_16x16x32_bf16 v[116:119], v[172:175], v[188:191], v[116:119]
	v_mfma_f32_16x16x32_bf16 v[112:115], v[180:183], v[188:191], v[112:115]
	v_mfma_f32_16x16x32_bf16 v[100:103], v[172:175], v[196:199], v[100:103]
	v_mfma_f32_16x16x32_bf16 v[96:99], v[180:183], v[196:199], v[96:99]
	v_mfma_f32_16x16x32_bf16 v[84:87], v[172:175], v[204:207], v[84:87]
	v_mfma_f32_16x16x32_bf16 v[80:83], v[180:183], v[204:207], v[80:83]
	v_mfma_f32_16x16x32_bf16 v[68:71], v[172:175], v[212:215], v[68:71]
	v_mfma_f32_16x16x32_bf16 v[64:67], v[180:183], v[212:215], v[64:67]
	s_setprio 0
	s_barrier
	s_mov_b32 m0, s38
	v_lshl_add_u64 v[216:217], s[52:53], 0, v[130:131]
	ds_read_b128 v[184:187], v152 offset:16384
	ds_read_b128 v[188:191], v152 offset:17408
	ds_read_b128 v[192:195], v152 offset:18432
	ds_read_b128 v[196:199], v152 offset:19456
	ds_read_b128 v[200:203], v152 offset:20480
	ds_read_b128 v[204:207], v152 offset:21504
	ds_read_b128 v[208:211], v152 offset:22528
	ds_read_b128 v[212:215], v152 offset:23552
	global_load_lds_dwordx4 v[216:217], off
	v_lshl_add_u64 v[218:219], s[52:53], 0, v[134:135]
	s_mov_b32 m0, s30
	v_lshl_add_u64 v[220:221], s[54:55], 0, v[130:131]
	global_load_lds_dwordx4 v[218:219], off
	s_mov_b32 m0, s33
	v_lshl_add_u64 v[222:223], s[50:51], 0, v[132:133]
	global_load_lds_dwordx4 v[220:221], off
	v_lshl_add_u64 v[220:221], s[54:55], 0, v[134:135]
	s_mov_b32 m0, s31
	s_nop 0
	global_load_lds_dwordx4 v[220:221], off
	v_lshl_add_u64 v[220:221], s[50:51], 0, v[128:129]
	s_mov_b32 m0, s47
	s_nop 0
	global_load_lds_dwordx4 v[220:221], off
	s_mov_b32 m0, s59
	s_nop 0
	global_load_lds_dwordx4 v[222:223], off
	s_waitcnt vmcnt(8)
	s_waitcnt lgkmcnt(0)
	s_barrier
	s_setprio 1
	s_waitcnt lgkmcnt(0)
	v_mfma_f32_16x16x32_bf16 v[60:63], v[142:145], v[184:187], 0
	v_mfma_f32_16x16x32_bf16 v[56:59], v[160:163], v[184:187], 0
	v_mfma_f32_16x16x32_bf16 v[44:47], v[142:145], v[192:195], 0
	v_mfma_f32_16x16x32_bf16 v[40:43], v[160:163], v[192:195], 0
	v_mfma_f32_16x16x32_bf16 v[28:31], v[142:145], v[200:203], 0
	v_mfma_f32_16x16x32_bf16 v[24:27], v[160:163], v[200:203], 0
	v_mfma_f32_16x16x32_bf16 v[12:15], v[142:145], v[208:211], 0
	v_mfma_f32_16x16x32_bf16 v[8:11], v[160:163], v[208:211], 0
	v_mfma_f32_16x16x32_bf16 v[60:63], v[156:159], v[188:191], v[60:63]
	v_mfma_f32_16x16x32_bf16 v[56:59], v[164:167], v[188:191], v[56:59]
	v_mfma_f32_16x16x32_bf16 v[44:47], v[156:159], v[196:199], v[44:47]
	v_mfma_f32_16x16x32_bf16 v[40:43], v[164:167], v[196:199], v[40:43]
	v_mfma_f32_16x16x32_bf16 v[28:31], v[156:159], v[204:207], v[28:31]
	v_mfma_f32_16x16x32_bf16 v[24:27], v[164:167], v[204:207], v[24:27]
	v_mfma_f32_16x16x32_bf16 v[12:15], v[156:159], v[212:215], v[12:15]
	v_mfma_f32_16x16x32_bf16 v[8:11], v[164:167], v[212:215], v[8:11]
	s_setprio 0
	s_setprio 1
	v_mfma_f32_16x16x32_bf16 v[52:55], v[168:171], v[184:187], 0
	v_mfma_f32_16x16x32_bf16 v[48:51], v[176:179], v[184:187], 0
	v_mfma_f32_16x16x32_bf16 v[36:39], v[168:171], v[192:195], 0
	v_mfma_f32_16x16x32_bf16 v[32:35], v[176:179], v[192:195], 0
	v_mfma_f32_16x16x32_bf16 v[20:23], v[168:171], v[200:203], 0
	v_mfma_f32_16x16x32_bf16 v[16:19], v[176:179], v[200:203], 0
	v_mfma_f32_16x16x32_bf16 v[4:7], v[168:171], v[208:211], 0
	v_mfma_f32_16x16x32_bf16 v[0:3], v[176:179], v[208:211], 0
	v_mfma_f32_16x16x32_bf16 v[52:55], v[172:175], v[188:191], v[52:55]
	v_mfma_f32_16x16x32_bf16 v[48:51], v[180:183], v[188:191], v[48:51]
	v_mfma_f32_16x16x32_bf16 v[36:39], v[172:175], v[196:199], v[36:39]
	v_mfma_f32_16x16x32_bf16 v[32:35], v[180:183], v[196:199], v[32:35]
	v_mfma_f32_16x16x32_bf16 v[20:23], v[172:175], v[204:207], v[20:23]
	v_mfma_f32_16x16x32_bf16 v[16:19], v[180:183], v[204:207], v[16:19]
	v_mfma_f32_16x16x32_bf16 v[4:7], v[172:175], v[212:215], v[4:7]
	v_mfma_f32_16x16x32_bf16 v[0:3], v[180:183], v[212:215], v[0:3]
	s_setprio 0
	s_barrier
	s_branch .Lkmid_P11

; #define PG8_STAGE(bufoff, gbase, voff) do { _Pragma("unroll") for (int _i = 0; _i < 2; ++_i) \
;         __builtin_amdgcn_global_load_lds((const unsigned*)((const char*)(gbase) + (voff)[_i]), (PG8_LAS unsigned*)(lds + (bufoff) + ldsw + _i * 8192), 16, 0, PG8_LOAD_AUX); } while (0)
; #define PG8_LDA(dst, b, h) do { _Pragma("unroll") for (int m = 0; m < 4; ++m) _Pragma("unroll") for (int k = 0; k < 2; ++k) dst[m][k] = *(const PG8_LAS bf16x8*)(lds + PG8_SA(b, h) + aoff + m * 2048 + k * 1024); } while (0)
; #define PG8_LDB(dst, b, h) do { _Pragma("unroll") for (int n = 0; n < 2; ++n) _Pragma("unroll") for (int k = 0; k < 2; ++k) dst[n][k] = *(const PG8_LAS bf16x8*)(lds + PG8_SB(b, h) + boff + n * 2048 + k * 1024); } while (0)
; #define PG8_SCHED __builtin_amdgcn_sched_barrier(0)
;     __host__ __device__ bool next(int i, Unit& u) const {
;         const long L = (long)i * G + c; if (L >= nwg) return false;
;         int wgid = (int)L; { const int q = nwg / NXCD, r = nwg % NXCD, xcd = wgid % NXCD, off = wgid / NXCD; wgid = (xcd < r ? xcd * (q + 1) : r * (q + 1) + (xcd - r) * q) + off; }
;         const int nig = WGM * nN, gid = wgid / nig, fm = gid * WGM, gsz = (nM - fm) < WGM ? (nM - fm) : WGM;
;         u.pm = fm + ((wgid % nig) % gsz); u.pn = (wgid % nig) / gsz; return true;
; template <class Epi, class Sched, bool ALIGN_EPI = false, bool SP2 = false>
; __device__ __forceinline__ void gemm_phase(PG8_LAS unsigned char* lds, const Gemm g, const Sched& S, const Epi& E) {
;     ...
;         const bool has_next = S.next(ui + 1, nxt);
;         const char* nA = has_next ? (const char*)g.A + (size_t)nxt.pm * tstepA + (size_t)nxt.pn * apn : cA; const char* nB = has_next ? (const char*)g.Bt + (size_t)nxt.pn * tstepB : cB;
;         for (int t = 0; t < nt; t += 2) {
;             const bool last = (t == nt - 2);
;             const char* a1 = cA + (size_t)(t + 1) * kstep;
;             const char* a2 = last ? nA : cA + (size_t)(t + 2) * kstep; const char* b2 = last ? nB : cB + (size_t)(t + 2) * kstep;
;             const char* a3 = a2 + kstep; const char* b3 = b2 + kstep;
;             if (last && has_next) S.a_ready(nxt);
;             if constexpr (SP2) {
;             PG8_LDB(B0, 0, 0); PG8_LDB(B1, 0, 1); PG8_SCHED; PG8_LDA(At, 0, 0); PG8_STAGE(PG8_SA(1, 1), a1 + hstepA, voffA);
.LBB0_1108:
	ds_read_b128 v[146:149], v157
	ds_read_b128 v[162:165], v157 offset:1024
	ds_read_b128 v[166:169], v157 offset:2048
	ds_read_b128 v[170:173], v157 offset:3072
	ds_read_b128 v[174:177], v158
	ds_read_b128 v[178:181], v158 offset:1024
	ds_read_b128 v[182:185], v158 offset:2048
	ds_read_b128 v[186:189], v158 offset:3072
	ds_read_b128 v[190:193], v159
	ds_read_b128 v[194:197], v159 offset:1024
	ds_read_b128 v[198:201], v159 offset:2048
	ds_read_b128 v[202:205], v159 offset:3072
	ds_read_b128 v[206:209], v159 offset:4096
	ds_read_b128 v[210:213], v159 offset:5120
	ds_read_b128 v[214:217], v159 offset:6144
	ds_read_b128 v[218:221], v159 offset:7168
	s_add_i32 s49, s49, 1
	s_mul_i32 s2, s49, s52
	s_mul_hi_u32 s3, s49, s53
	s_add_i32 s3, s3, s2
	s_mul_i32 s2, s49, s53
	v_readlane_b32 s15, v239, 0
	s_add_u32 s18, s2, s15
	s_addc_u32 s19, s3, s43
	v_cmp_gt_i64_e32 vcc, s[18:19], v[144:145]
	v_cmp_lt_i64_e64 s[2:3], s[18:19], v[142:143]
	s_cbranch_vccnz .LBB0_1110
	s_ashr_i32 s14, s18, 31
	s_lshr_b32 s14, s14, 29
	s_add_i32 s14, s18, s14
	s_ashr_i32 s15, s14, 3
	s_and_b32 s14, s14, -8
	s_sub_i32 s14, s18, s14
	s_cmp_lt_i32 s14, 0
	s_cselect_b32 s16, s44, 0x160
	s_mul_i32 s14, s14, s16
	s_add_i32 s14, s14, s15
	s_mul_hi_i32 s15, s14, 0x2e8ba2e9
	s_lshr_b32 s16, s15, 31
	s_ashr_i32 s15, s15, 4
	s_add_i32 s15, s15, s16
	s_lshl_b32 s16, s15, 2
	s_sub_i32 s17, 0x80, s16
	s_min_i32 s17, s17, 4
	s_abs_i32 s18, s17
	v_cvt_f32_u32_e32 v0, s18
	s_sub_i32 s24, 0, s18
	s_mulk_i32 s15, 0x58
	s_sub_i32 s15, s14, s15
	v_rcp_iflag_f32_e32 v0, v0
	s_abs_i32 s14, s15
	s_xor_b32 s19, s15, s17
	s_ashr_i32 s19, s19, 31
	v_mul_f32_e32 v0, 0x4f7ffffe, v0
	v_cvt_u32_f32_e32 v0, v0
	s_nop 0
	v_readfirstlane_b32 s25, v0
	s_mul_i32 s24, s24, s25
	s_mul_hi_u32 s24, s25, s24
	s_add_i32 s25, s25, s24
	s_mul_hi_u32 s24, s14, s25
	s_mul_i32 s25, s24, s18
	s_sub_i32 s14, s14, s25
	s_add_i32 s26, s24, 1
	s_sub_i32 s25, s14, s18
	s_cmp_ge_u32 s14, s18
	s_cselect_b32 s24, s26, s24
	s_cselect_b32 s14, s25, s14
	s_add_i32 s25, s24, 1
	s_cmp_ge_u32 s14, s18
	s_cselect_b32 s14, s25, s24
	s_xor_b32 s14, s14, s19
	s_sub_i32 s14, s14, s19
	s_mul_i32 s17, s14, s17
	s_sub_i32 s15, s15, s17
	s_add_i32 s16, s16, s15
; #define PG8_STAGE(bufoff, gbase, voff) do { _Pragma("unroll") for (int _i = 0; _i < 2; ++_i) \
;         __builtin_amdgcn_global_load_lds((const unsigned*)((const char*)(gbase) + (voff)[_i]), (PG8_LAS unsigned*)(lds + (bufoff) + ldsw + _i * 8192), 16, 0, PG8_LOAD_AUX); } while (0)
; #define PG8_LDA(dst, b, h) do { _Pragma("unroll") for (int m = 0; m < 4; ++m) _Pragma("unroll") for (int k = 0; k < 2; ++k) dst[m][k] = *(const PG8_LAS bf16x8*)(lds + PG8_SA(b, h) + aoff + m * 2048 + k * 1024); } while (0)
; #define PG8_LDB(dst, b, h) do { _Pragma("unroll") for (int n = 0; n < 2; ++n) _Pragma("unroll") for (int k = 0; k < 2; ++k) dst[n][k] = *(const PG8_LAS bf16x8*)(lds + PG8_SB(b, h) + boff + n * 2048 + k * 1024); } while (0)
; #define PG8_WAIT_V(n) asm volatile("s_waitcnt vmcnt(" #n ")" ::: "memory")
; #define PG8_WAIT_L(n) asm volatile("s_waitcnt lgkmcnt(" #n ")" ::: "memory")
; #define PG8_BAR __builtin_amdgcn_s_barrier()
; #define PG8_SCHED __builtin_amdgcn_sched_barrier(0)
; template <class Epi, class Sched, bool ALIGN_EPI = false, bool SP2 = false>
; __device__ __forceinline__ void gemm_phase(PG8_LAS unsigned char* lds, const Gemm g, const Sched& S, const Epi& E) {
;     ...
;         const char* nA = has_next ? (const char*)g.A + (size_t)nxt.pm * tstepA + (size_t)nxt.pn * apn : cA; const char* nB = has_next ? (const char*)g.Bt + (size_t)nxt.pn * tstepB : cB;
;         for (int t = 0; t < nt; t += 2) {
;             const bool last = (t == nt - 2);
;             const char* a1 = cA + (size_t)(t + 1) * kstep;
;             const char* a2 = last ? nA : cA + (size_t)(t + 2) * kstep; const char* b2 = last ? nB : cB + (size_t)(t + 2) * kstep;
;             const char* a3 = a2 + kstep; const char* b3 = b2 + kstep;
;             if (last && has_next) S.a_ready(nxt);
;             if constexpr (SP2) {
;             PG8_LDB(B0, 0, 0); PG8_LDB(B1, 0, 1); PG8_SCHED; PG8_LDA(At, 0, 0); PG8_STAGE(PG8_SA(1, 1), a1 + hstepA, voffA);
;             PG8_WAIT_V(8); PG8_WAIT_L(0); PG8_BAR; PG8_MMA(0, 0, At, B0); PG8_MMA(0, 1, At, B1); PG8_BAR; PG8_SCHED;
;             PG8_LDA(At, 0, 1); PG8_STAGE(PG8_SB(0, 0), b2, voffB); PG8_STAGE(PG8_SB(0, 1), b2 + hstepB, voffB); PG8_STAGE(PG8_SA(0, 0), a2, voffA);
;             PG8_WAIT_V(8); PG8_WAIT_L(0); PG8_BAR; PG8_MMA(1, 0, At, B0); PG8_MMA(1, 1, At, B1); PG8_BAR; PG8_SCHED;
.LBB0_1110:
	s_ashr_i32 s17, s16, 31
	s_lshl_b64 s[18:19], s[16:17], 19
	s_add_u32 s18, s30, s18
	s_addc_u32 s19, s31, s19
	s_and_b64 s[24:25], s[2:3], exec
	s_cselect_b32 s17, s19, s21
	s_cselect_b32 s24, s18, s20
	s_ashr_i32 s15, s14, 31
	s_lshl_b64 s[26:27], s[14:15], 19
	s_add_u32 s36, s40, s26
	s_addc_u32 s37, s41, s27
	s_and_b64 s[26:27], s[2:3], exec
	s_cselect_b32 s15, s37, s23
	s_cselect_b32 s25, s36, s22
	s_add_u32 s20, s20, 0x40080
	s_addc_u32 s21, s21, 0
	s_add_u32 s26, s22, 0x100
	s_addc_u32 s27, s23, 0
	s_mov_b32 s28, -2
	s_add_u32 s22, s20, 0xfffc0080
	s_addc_u32 s23, s21, -1
	s_cmp_eq_u32 s28, 12
	s_cselect_b32 s35, s17, s23
	s_cselect_b32 s34, s24, s22
	s_cselect_b32 s23, s15, s27
	s_cselect_b32 s22, s25, s26
	v_lshl_add_u64 v[150:151], s[20:21], 0, v[138:139]
	s_add_i32 m0, s45, 0xc000
	global_load_lds_dwordx4 v[150:151], off
	v_lshl_add_u64 v[150:151], s[20:21], 0, v[140:141]
	s_add_i32 m0, s45, 0xe000
	s_nop 0
	global_load_lds_dwordx4 v[150:151], off
	s_waitcnt vmcnt(8)
	s_waitcnt lgkmcnt(0)
	s_barrier
	s_setprio 1
	s_waitcnt lgkmcnt(0)
	v_mfma_f32_16x16x32_bf16 v[124:127], v[146:149], v[190:193], 0
	v_mfma_f32_16x16x32_bf16 v[120:123], v[166:169], v[190:193], 0
	v_mfma_f32_16x16x32_bf16 v[108:111], v[146:149], v[198:201], 0
	v_mfma_f32_16x16x32_bf16 v[104:107], v[166:169], v[198:201], 0
	v_mfma_f32_16x16x32_bf16 v[92:95], v[146:149], v[206:209], 0
	v_mfma_f32_16x16x32_bf16 v[88:91], v[166:169], v[206:209], 0
	v_mfma_f32_16x16x32_bf16 v[76:79], v[146:149], v[214:217], 0
	v_mfma_f32_16x16x32_bf16 v[72:75], v[166:169], v[214:217], 0
	v_mfma_f32_16x16x32_bf16 v[124:127], v[162:165], v[194:197], v[124:127]
	v_mfma_f32_16x16x32_bf16 v[120:123], v[170:173], v[194:197], v[120:123]
	v_mfma_f32_16x16x32_bf16 v[108:111], v[162:165], v[202:205], v[108:111]
	v_mfma_f32_16x16x32_bf16 v[104:107], v[170:173], v[202:205], v[104:107]
	v_mfma_f32_16x16x32_bf16 v[92:95], v[162:165], v[210:213], v[92:95]
	v_mfma_f32_16x16x32_bf16 v[88:91], v[170:173], v[210:213], v[88:91]
	v_mfma_f32_16x16x32_bf16 v[76:79], v[162:165], v[218:221], v[76:79]
	v_mfma_f32_16x16x32_bf16 v[72:75], v[170:173], v[218:221], v[72:75]
	s_setprio 0
	s_setprio 1
	v_mfma_f32_16x16x32_bf16 v[116:119], v[174:177], v[190:193], 0
	v_mfma_f32_16x16x32_bf16 v[112:115], v[182:185], v[190:193], 0
	v_mfma_f32_16x16x32_bf16 v[100:103], v[174:177], v[198:201], 0
	v_mfma_f32_16x16x32_bf16 v[96:99], v[182:185], v[198:201], 0
	v_mfma_f32_16x16x32_bf16 v[84:87], v[174:177], v[206:209], 0
	v_mfma_f32_16x16x32_bf16 v[80:83], v[182:185], v[206:209], 0
	v_mfma_f32_16x16x32_bf16 v[68:71], v[174:177], v[214:217], 0
	v_mfma_f32_16x16x32_bf16 v[64:67], v[182:185], v[214:217], 0
	v_mfma_f32_16x16x32_bf16 v[116:119], v[178:181], v[194:197], v[116:119]
	v_mfma_f32_16x16x32_bf16 v[112:115], v[186:189], v[194:197], v[112:115]
	v_mfma_f32_16x16x32_bf16 v[100:103], v[178:181], v[202:205], v[100:103]
	v_mfma_f32_16x16x32_bf16 v[96:99], v[186:189], v[202:205], v[96:99]
	v_mfma_f32_16x16x32_bf16 v[84:87], v[178:181], v[210:213], v[84:87]
	v_mfma_f32_16x16x32_bf16 v[80:83], v[186:189], v[210:213], v[80:83]
	v_mfma_f32_16x16x32_bf16 v[68:71], v[178:181], v[218:221], v[68:71]
	v_mfma_f32_16x16x32_bf16 v[64:67], v[186:189], v[218:221], v[64:67]
	s_setprio 0
	s_barrier
	s_add_i32 s29, s54, s42
	v_lshl_add_u64 v[150:151], s[22:23], 0, v[132:133]
	s_mov_b32 m0, s29
	ds_read_b128 v[190:193], v159 offset:16384
	ds_read_b128 v[194:197], v159 offset:17408
	ds_read_b128 v[198:201], v159 offset:18432
	ds_read_b128 v[202:205], v159 offset:19456
	ds_read_b128 v[206:209], v159 offset:20480
	ds_read_b128 v[210:213], v159 offset:21504
	ds_read_b128 v[214:217], v159 offset:22528
	ds_read_b128 v[218:221], v159 offset:23552
	global_load_lds_dwordx4 v[150:151], off
	s_add_i32 m0, s29, 0x2000
	s_add_u32 s30, s22, 0x40000
	v_lshl_add_u64 v[222:223], s[22:23], 0, v[128:129]
	s_addc_u32 s31, s23, 0
	s_add_i32 s29, s55, s42
	global_load_lds_dwordx4 v[222:223], off
	v_lshl_add_u64 v[224:225], s[30:31], 0, v[132:133]
	s_mov_b32 m0, s29
	v_lshl_add_u64 v[226:227], s[34:35], 0, v[130:131]
	global_load_lds_dwordx4 v[224:225], off
	v_lshl_add_u64 v[224:225], s[30:31], 0, v[128:129]
	s_add_i32 m0, s29, 0x2000
	s_nop 0
	global_load_lds_dwordx4 v[224:225], off
	v_lshl_add_u64 v[224:225], s[34:35], 0, v[134:135]
	s_mov_b32 m0, s45
	s_nop 0
	global_load_lds_dwordx4 v[224:225], off
	s_mov_b32 m0, s46
	s_nop 0
	global_load_lds_dwordx4 v[226:227], off
	s_waitcnt vmcnt(8)
	s_waitcnt lgkmcnt(0)
	s_barrier
	s_setprio 1
	s_waitcnt lgkmcnt(0)
	v_mfma_f32_16x16x32_bf16 v[60:63], v[146:149], v[190:193], 0
	v_mfma_f32_16x16x32_bf16 v[56:59], v[166:169], v[190:193], 0
	v_mfma_f32_16x16x32_bf16 v[44:47], v[146:149], v[198:201], 0
	v_mfma_f32_16x16x32_bf16 v[40:43], v[166:169], v[198:201], 0
	v_mfma_f32_16x16x32_bf16 v[28:31], v[146:149], v[206:209], 0
	v_mfma_f32_16x16x32_bf16 v[24:27], v[166:169], v[206:209], 0
	v_mfma_f32_16x16x32_bf16 v[12:15], v[146:149], v[214:217], 0
	v_mfma_f32_16x16x32_bf16 v[8:11], v[166:169], v[214:217], 0
	v_mfma_f32_16x16x32_bf16 v[60:63], v[162:165], v[194:197], v[60:63]
	v_mfma_f32_16x16x32_bf16 v[56:59], v[170:173], v[194:197], v[56:59]
	v_mfma_f32_16x16x32_bf16 v[44:47], v[162:165], v[202:205], v[44:47]
	v_mfma_f32_16x16x32_bf16 v[40:43], v[170:173], v[202:205], v[40:43]
	v_mfma_f32_16x16x32_bf16 v[28:31], v[162:165], v[210:213], v[28:31]
	v_mfma_f32_16x16x32_bf16 v[24:27], v[170:173], v[210:213], v[24:27]
	v_mfma_f32_16x16x32_bf16 v[12:15], v[162:165], v[218:221], v[12:15]
	v_mfma_f32_16x16x32_bf16 v[8:11], v[170:173], v[218:221], v[8:11]
	s_setprio 0
	s_setprio 1
	v_mfma_f32_16x16x32_bf16 v[52:55], v[174:177], v[190:193], 0
	v_mfma_f32_16x16x32_bf16 v[48:51], v[182:185], v[190:193], 0
	v_mfma_f32_16x16x32_bf16 v[36:39], v[174:177], v[198:201], 0
	v_mfma_f32_16x16x32_bf16 v[32:35], v[182:185], v[198:201], 0
	v_mfma_f32_16x16x32_bf16 v[20:23], v[174:177], v[206:209], 0
	v_mfma_f32_16x16x32_bf16 v[16:19], v[182:185], v[206:209], 0
	v_mfma_f32_16x16x32_bf16 v[4:7], v[174:177], v[214:217], 0
	v_mfma_f32_16x16x32_bf16 v[0:3], v[182:185], v[214:217], 0
	v_mfma_f32_16x16x32_bf16 v[52:55], v[178:181], v[194:197], v[52:55]
	v_mfma_f32_16x16x32_bf16 v[48:51], v[186:189], v[194:197], v[48:51]
	v_mfma_f32_16x16x32_bf16 v[36:39], v[178:181], v[202:205], v[36:39]
	v_mfma_f32_16x16x32_bf16 v[32:35], v[186:189], v[202:205], v[32:35]
	v_mfma_f32_16x16x32_bf16 v[20:23], v[178:181], v[210:213], v[20:23]
	v_mfma_f32_16x16x32_bf16 v[16:19], v[186:189], v[210:213], v[16:19]
	v_mfma_f32_16x16x32_bf16 v[4:7], v[178:181], v[218:221], v[4:7]
	v_mfma_f32_16x16x32_bf16 v[0:3], v[186:189], v[218:221], v[0:3]
	s_setprio 0
	s_barrier
	s_branch .Lkmid_P12

; #define PG8_STAGE(bufoff, gbase, voff) do { _Pragma("unroll") for (int _i = 0; _i < 2; ++_i) \
;         __builtin_amdgcn_global_load_lds((const unsigned*)((const char*)(gbase) + (voff)[_i]), (PG8_LAS unsigned*)(lds + (bufoff) + ldsw + _i * 8192), 16, 0, PG8_LOAD_AUX); } while (0)
; #define PG8_LDA(dst, b, h) do { _Pragma("unroll") for (int m = 0; m < 4; ++m) _Pragma("unroll") for (int k = 0; k < 2; ++k) dst[m][k] = *(const PG8_LAS bf16x8*)(lds + PG8_SA(b, h) + aoff + m * 2048 + k * 1024); } while (0)
; #define PG8_LDB(dst, b, h) do { _Pragma("unroll") for (int n = 0; n < 2; ++n) _Pragma("unroll") for (int k = 0; k < 2; ++k) dst[n][k] = *(const PG8_LAS bf16x8*)(lds + PG8_SB(b, h) + boff + n * 2048 + k * 1024); } while (0)
; #define PG8_SCHED __builtin_amdgcn_sched_barrier(0)
;     __host__ __device__ bool next(int i, Unit& u) const {
;         const long L = (long)i * G + c; if (L >= nwg) return false;
;         int wgid = (int)L; { const int q = nwg / NXCD, r = nwg % NXCD, xcd = wgid % NXCD, off = wgid / NXCD; wgid = (xcd < r ? xcd * (q + 1) : r * (q + 1) + (xcd - r) * q) + off; }
; template <class Epi, class Sched, bool ALIGN_EPI = false, bool SP2 = false>
; __device__ __forceinline__ void gemm_phase(PG8_LAS unsigned char* lds, const Gemm g, const Sched& S, const Epi& E) {
;     ...
;             if constexpr (SP2) {
;             PG8_LDB(B0, 0, 0); PG8_LDB(B1, 0, 1); PG8_SCHED; PG8_LDA(At, 0, 0); PG8_STAGE(PG8_SA(1, 1), a1 + hstepA, voffA);
.LBB0_1185:
	ds_read_b128 v[146:149], v155
	ds_read_b128 v[160:163], v155 offset:1024
	ds_read_b128 v[164:167], v155 offset:2048
	ds_read_b128 v[168:171], v155 offset:3072
	ds_read_b128 v[172:175], v156
	ds_read_b128 v[176:179], v156 offset:1024
	ds_read_b128 v[180:183], v156 offset:2048
	ds_read_b128 v[184:187], v156 offset:3072
	ds_read_b128 v[188:191], v157
	ds_read_b128 v[192:195], v157 offset:1024
	ds_read_b128 v[196:199], v157 offset:2048
	ds_read_b128 v[200:203], v157 offset:3072
	ds_read_b128 v[204:207], v157 offset:4096
	ds_read_b128 v[208:211], v157 offset:5120
	ds_read_b128 v[212:215], v157 offset:6144
	ds_read_b128 v[216:219], v157 offset:7168
	s_add_i32 s57, s57, 1
	s_mul_i32 s6, s57, s52
	s_mul_hi_u32 s7, s57, s53
	s_add_i32 s7, s7, s6
	s_mul_i32 s6, s57, s53
	v_readlane_b32 s8, v239, 0
	s_add_u32 s6, s6, s8
	s_addc_u32 s7, s7, s54
	v_cmp_gt_i64_e32 vcc, s[6:7], v[144:145]
	v_cmp_lt_i64_e64 s[8:9], s[6:7], v[142:143]
	s_cbranch_vccnz .LBB0_1191
	s_ashr_i32 s7, s6, 31
	s_lshr_b32 s7, s7, 29
	s_add_i32 s22, s6, s7
	s_and_b32 s7, s22, -8
	s_sub_i32 s23, s6, s7
	s_cmp_gt_i32 s23, -1
	s_mov_b64 s[6:7], -1
	s_cbranch_scc0 .LBB0_1188
	s_lshl_b32 s25, s23, 6
	s_mov_b64 s[6:7], 0

; #define PG8_STAGE(bufoff, gbase, voff) do { _Pragma("unroll") for (int _i = 0; _i < 2; ++_i) \
;         __builtin_amdgcn_global_load_lds((const unsigned*)((const char*)(gbase) + (voff)[_i]), (PG8_LAS unsigned*)(lds + (bufoff) + ldsw + _i * 8192), 16, 0, PG8_LOAD_AUX); } while (0)
; #define PG8_LDA(dst, b, h) do { _Pragma("unroll") for (int m = 0; m < 4; ++m) _Pragma("unroll") for (int k = 0; k < 2; ++k) dst[m][k] = *(const PG8_LAS bf16x8*)(lds + PG8_SA(b, h) + aoff + m * 2048 + k * 1024); } while (0)
; template <class Epi, class Sched, bool ALIGN_EPI = false, bool SP2 = false>
; __device__ __forceinline__ void gemm_phase(PG8_LAS unsigned char* lds, const Gemm g, const Sched& S, const Epi& E) {
;     ...
;         const char* nA = has_next ? (const char*)g.A + (size_t)nxt.pm * tstepA + (size_t)nxt.pn * apn : cA; const char* nB = has_next ? (const char*)g.Bt + (size_t)nxt.pn * tstepB : cB;
;         for (int t = 0; t < nt; t += 2) {
;             const bool last = (t == nt - 2);
;             const char* a1 = cA + (size_t)(t + 1) * kstep;
;             const char* a2 = last ? nA : cA + (size_t)(t + 2) * kstep; const char* b2 = last ? nB : cB + (size_t)(t + 2) * kstep;
;             const char* a3 = a2 + kstep; const char* b3 = b2 + kstep;
;             if (last && has_next) S.a_ready(nxt);
;             if constexpr (SP2) {
;             PG8_LDB(B0, 0, 0); PG8_LDB(B1, 0, 1); PG8_SCHED; PG8_LDA(At, 0, 0); PG8_STAGE(PG8_SA(1, 1), a1 + hstepA, voffA);
;             PG8_WAIT_V(8); PG8_WAIT_L(0); PG8_BAR; PG8_MMA(0, 0, At, B0); PG8_MMA(0, 1, At, B1); PG8_BAR; PG8_SCHED;
;             PG8_LDA(At, 0, 1); PG8_STAGE(PG8_SB(0, 0), b2, voffB); PG8_STAGE(PG8_SB(0, 1), b2 + hstepB, voffB); PG8_STAGE(PG8_SA(0, 0), a2, voffA);
;             PG8_WAIT_V(8); PG8_WAIT_L(0); PG8_BAR; PG8_MMA(1, 0, At, B0); PG8_MMA(1, 1, At, B1); PG8_BAR; PG8_SCHED;
;             PG8_LDB(B0, 1, 0); PG8_LDB(B1, 1, 1); PG8_SCHED; PG8_LDA(At, 1, 0); PG8_STAGE(PG8_SA(0, 1), a2 + hstepA, voffA);
;             PG8_WAIT_V(8); PG8_WAIT_L(0); PG8_BAR; PG8_MMA(0, 0, At, B0); PG8_MMA(0, 1, At, B1); PG8_BAR; PG8_SCHED;
;             PG8_LDA(At, 1, 1); PG8_STAGE(PG8_SB(1, 0), b3, voffB); PG8_STAGE(PG8_SB(1, 1), b3 + hstepB, voffB); PG8_STAGE(PG8_SA(1, 0), a3, voffA);
;             PG8_WAIT_V(8); PG8_WAIT_L(0); PG8_BAR; PG8_MMA(1, 0, At, B0); PG8_MMA(1, 1, At, B1); PG8_BAR; PG8_SCHED;
.LBB0_1195:
	s_add_u32 s0, s0, 0xb0080
	s_addc_u32 s1, s1, 0
	s_add_u32 s25, s20, 0x100
	s_addc_u32 s26, s21, 0
	s_mov_b32 s27, -2
	s_waitcnt lgkmcnt(0)
	s_add_u32 s20, s0, 0xfff50080
	s_addc_u32 s21, s1, -1
	s_cmp_eq_u32 s27, 40
	s_cselect_b32 s23, s9, s21
	s_cselect_b32 s22, s8, s20
	s_cselect_b32 s21, s41, s26
	s_cselect_b32 s20, s40, s25
	v_lshl_add_u64 v[220:221], s[0:1], 0, v[138:139]
	s_add_i32 m0, s43, 0xc000
	global_load_lds_dwordx4 v[220:221], off
	v_lshl_add_u64 v[220:221], s[0:1], 0, v[140:141]
	s_add_i32 m0, s43, 0xe000
	s_nop 0
	global_load_lds_dwordx4 v[220:221], off
	s_waitcnt vmcnt(8)
	s_waitcnt lgkmcnt(0)
	s_barrier
	s_setprio 1
	s_waitcnt lgkmcnt(0)
	v_mfma_f32_16x16x32_bf16 v[124:127], v[146:149], v[188:191], 0
	v_mfma_f32_16x16x32_bf16 v[120:123], v[164:167], v[188:191], 0
	v_mfma_f32_16x16x32_bf16 v[108:111], v[146:149], v[196:199], 0
	v_mfma_f32_16x16x32_bf16 v[104:107], v[164:167], v[196:199], 0
	v_mfma_f32_16x16x32_bf16 v[92:95], v[146:149], v[204:207], 0
	v_mfma_f32_16x16x32_bf16 v[88:91], v[164:167], v[204:207], 0
	v_mfma_f32_16x16x32_bf16 v[76:79], v[146:149], v[212:215], 0
	v_mfma_f32_16x16x32_bf16 v[72:75], v[164:167], v[212:215], 0
	v_mfma_f32_16x16x32_bf16 v[124:127], v[160:163], v[192:195], v[124:127]
	v_mfma_f32_16x16x32_bf16 v[120:123], v[168:171], v[192:195], v[120:123]
	v_mfma_f32_16x16x32_bf16 v[108:111], v[160:163], v[200:203], v[108:111]
	v_mfma_f32_16x16x32_bf16 v[104:107], v[168:171], v[200:203], v[104:107]
	v_mfma_f32_16x16x32_bf16 v[92:95], v[160:163], v[208:211], v[92:95]
	v_mfma_f32_16x16x32_bf16 v[88:91], v[168:171], v[208:211], v[88:91]
	v_mfma_f32_16x16x32_bf16 v[76:79], v[160:163], v[216:219], v[76:79]
	v_mfma_f32_16x16x32_bf16 v[72:75], v[168:171], v[216:219], v[72:75]
	s_setprio 0
	s_setprio 1
	v_mfma_f32_16x16x32_bf16 v[116:119], v[172:175], v[188:191], 0
	v_mfma_f32_16x16x32_bf16 v[112:115], v[180:183], v[188:191], 0
	v_mfma_f32_16x16x32_bf16 v[100:103], v[172:175], v[196:199], 0
	v_mfma_f32_16x16x32_bf16 v[96:99], v[180:183], v[196:199], 0
	v_mfma_f32_16x16x32_bf16 v[84:87], v[172:175], v[204:207], 0
	v_mfma_f32_16x16x32_bf16 v[80:83], v[180:183], v[204:207], 0
	v_mfma_f32_16x16x32_bf16 v[68:71], v[172:175], v[212:215], 0
	v_mfma_f32_16x16x32_bf16 v[64:67], v[180:183], v[212:215], 0
	v_mfma_f32_16x16x32_bf16 v[116:119], v[176:179], v[192:195], v[116:119]
	v_mfma_f32_16x16x32_bf16 v[112:115], v[184:187], v[192:195], v[112:115]
	v_mfma_f32_16x16x32_bf16 v[100:103], v[176:179], v[200:203], v[100:103]
	v_mfma_f32_16x16x32_bf16 v[96:99], v[184:187], v[200:203], v[96:99]
	v_mfma_f32_16x16x32_bf16 v[84:87], v[176:179], v[208:211], v[84:87]
	v_mfma_f32_16x16x32_bf16 v[80:83], v[184:187], v[208:211], v[80:83]
	v_mfma_f32_16x16x32_bf16 v[68:71], v[176:179], v[216:219], v[68:71]
	v_mfma_f32_16x16x32_bf16 v[64:67], v[184:187], v[216:219], v[64:67]
	s_setprio 0
	s_barrier
	s_add_i32 s28, s55, s42
	v_lshl_add_u64 v[220:221], s[20:21], 0, v[130:131]
	s_mov_b32 m0, s28
	ds_read_b128 v[188:191], v157 offset:16384
	ds_read_b128 v[192:195], v157 offset:17408
	ds_read_b128 v[196:199], v157 offset:18432
	ds_read_b128 v[200:203], v157 offset:19456
	ds_read_b128 v[204:207], v157 offset:20480
	ds_read_b128 v[208:211], v157 offset:21504
	ds_read_b128 v[212:215], v157 offset:22528
	ds_read_b128 v[216:219], v157 offset:23552
	global_load_lds_dwordx4 v[220:221], off
	s_add_i32 m0, s28, 0x2000
	s_add_u32 s28, s20, 0x2c000
	v_lshl_add_u64 v[222:223], s[20:21], 0, v[134:135]
	s_addc_u32 s29, s21, 0
	s_add_i32 s30, s56, s42
	global_load_lds_dwordx4 v[222:223], off
	v_lshl_add_u64 v[224:225], s[28:29], 0, v[130:131]
	s_mov_b32 m0, s30
	v_lshl_add_u64 v[226:227], s[22:23], 0, v[132:133]
	global_load_lds_dwordx4 v[224:225], off
	v_lshl_add_u64 v[224:225], s[28:29], 0, v[134:135]
	s_add_i32 m0, s30, 0x2000
	s_nop 0
	global_load_lds_dwordx4 v[224:225], off
	v_lshl_add_u64 v[224:225], s[22:23], 0, v[128:129]
	s_mov_b32 m0, s43
	s_nop 0
	global_load_lds_dwordx4 v[224:225], off
	s_mov_b32 m0, s44
	s_nop 0
	global_load_lds_dwordx4 v[226:227], off
	s_waitcnt vmcnt(8)
	s_waitcnt lgkmcnt(0)
	s_barrier
	s_setprio 1
	s_waitcnt lgkmcnt(0)
	v_mfma_f32_16x16x32_bf16 v[60:63], v[146:149], v[188:191], 0
	v_mfma_f32_16x16x32_bf16 v[56:59], v[164:167], v[188:191], 0
	v_mfma_f32_16x16x32_bf16 v[44:47], v[146:149], v[196:199], 0
	v_mfma_f32_16x16x32_bf16 v[40:43], v[164:167], v[196:199], 0
	v_mfma_f32_16x16x32_bf16 v[28:31], v[146:149], v[204:207], 0
	v_mfma_f32_16x16x32_bf16 v[24:27], v[164:167], v[204:207], 0
	v_mfma_f32_16x16x32_bf16 v[12:15], v[146:149], v[212:215], 0
	v_mfma_f32_16x16x32_bf16 v[8:11], v[164:167], v[212:215], 0
	v_mfma_f32_16x16x32_bf16 v[60:63], v[160:163], v[192:195], v[60:63]
	v_mfma_f32_16x16x32_bf16 v[56:59], v[168:171], v[192:195], v[56:59]
	v_mfma_f32_16x16x32_bf16 v[44:47], v[160:163], v[200:203], v[44:47]
	v_mfma_f32_16x16x32_bf16 v[40:43], v[168:171], v[200:203], v[40:43]
	v_mfma_f32_16x16x32_bf16 v[28:31], v[160:163], v[208:211], v[28:31]
	v_mfma_f32_16x16x32_bf16 v[24:27], v[168:171], v[208:211], v[24:27]
	v_mfma_f32_16x16x32_bf16 v[12:15], v[160:163], v[216:219], v[12:15]
	v_mfma_f32_16x16x32_bf16 v[8:11], v[168:171], v[216:219], v[8:11]
	s_setprio 0
	s_setprio 1
	v_mfma_f32_16x16x32_bf16 v[52:55], v[172:175], v[188:191], 0
	v_mfma_f32_16x16x32_bf16 v[48:51], v[180:183], v[188:191], 0
	v_mfma_f32_16x16x32_bf16 v[36:39], v[172:175], v[196:199], 0
	v_mfma_f32_16x16x32_bf16 v[32:35], v[180:183], v[196:199], 0
	v_mfma_f32_16x16x32_bf16 v[20:23], v[172:175], v[204:207], 0
	v_mfma_f32_16x16x32_bf16 v[16:19], v[180:183], v[204:207], 0
	v_mfma_f32_16x16x32_bf16 v[4:7], v[172:175], v[212:215], 0
	v_mfma_f32_16x16x32_bf16 v[0:3], v[180:183], v[212:215], 0
	v_mfma_f32_16x16x32_bf16 v[52:55], v[176:179], v[192:195], v[52:55]
	v_mfma_f32_16x16x32_bf16 v[48:51], v[184:187], v[192:195], v[48:51]
	v_mfma_f32_16x16x32_bf16 v[36:39], v[176:179], v[200:203], v[36:39]
	v_mfma_f32_16x16x32_bf16 v[32:35], v[184:187], v[200:203], v[32:35]
	v_mfma_f32_16x16x32_bf16 v[20:23], v[176:179], v[208:211], v[20:23]
	v_mfma_f32_16x16x32_bf16 v[16:19], v[184:187], v[208:211], v[16:19]
	v_mfma_f32_16x16x32_bf16 v[4:7], v[176:179], v[216:219], v[4:7]
	v_mfma_f32_16x16x32_bf16 v[0:3], v[184:187], v[216:219], v[0:3]
	s_setprio 0
	s_barrier
	s_branch .Lkmid_P13
